# P4 and P10 epilogues: all eight LayerNorm row-sum pairs of a tile fetched up front instead of one store-ack round trip per row
# baseline (speedup 1.0000x reference)
; __device__ __forceinline__ float sigmoidf_(float x) { return __builtin_amdgcn_rcpf(1.0f + __expf(-x)); }
; __device__ __forceinline__ float gelu_tanh(float x) { return x * sigmoidf_(1.5957691216057308f * (x + 0.044715f * x * x * x)); }
; __device__ __forceinline__ f32x2 ln_stats(f32x2 sm) { const float mu = sm[0] * (1.f / D); const float var = fmaxf(sm[1] * (1.f / D) - mu * mu, 0.f); return (f32x2){mu, 1.0f / sqrtf(var + LN_EPS)}; }
;     __device__ __forceinline__ void operator()(const f32x4 (&acc)[2][2][4][2], const Unit& u, int wr, int wc, int fr, int fq) const {
;     ...
;             for (int bj = 0; bj < 2; ++bj)
; #pragma unroll
;                 for (int n = 0; n < 2; ++n) { s1[bj][n] = *(const f32x4*)(cs + col0 + bj * HALF + 4 * n); s2[bj][n] = *(const f32x4*)(cs + NZ + col0 + bj * HALF + 4 * n); }
; #pragma unroll
;             for (int ai = 0; ai < 2; ++ai)
; #pragma unroll
;                 for (int m = 0; m < 4; ++m) {
;                     const int r = row0 + ai * HALF + m * 16;
;                     bf16_t* rowp = Z + (size_t)r * NZ + col0;
;                     const f32x2 st = ln_stats(*(const f32x2*)(rsum + 2 * (size_t)r));
; #pragma unroll
;                     for (int bj = 0; bj < 2; ++bj) {
;                         f32x4 v0 = (acc[ai][bj][m][0] - s1[bj][0] * st[0]) * st[1] + s2[bj][0], v1 = (acc[ai][bj][m][1] - s1[bj][1] * st[0]) * st[1] + s2[bj][1];
;                         if (mode == 1) {
; #pragma unroll
;                             for (int j = 0; j < 4; ++j) { v0[j] = gelu_tanh(v0[j]); v1[j] = gelu_tanh(v1[j]); }
;                         } else if (mode == 2) {
; #pragma unroll
;                             for (int j = 0; j < 4; ++j) { v0[j] = sigmoidf_(v0[j] + gb[bj][0][j]); v1[j] = sigmoidf_(v1[j] + gb[bj][1][j]); }
.LBB0_406:
	v_lshl_add_u64 v[50:51], v[198:199], 3, s[54:55]
	global_load_dwordx2 v[206:207], v[50:51], off
	global_load_dwordx2 v[238:239], v[50:51], off offset:128
	global_load_dwordx2 v[240:241], v[50:51], off offset:256
	global_load_dwordx2 v[242:243], v[50:51], off offset:384
	global_load_dwordx2 v[244:245], v[50:51], off offset:1024
	global_load_dwordx2 v[246:247], v[50:51], off offset:1152
	global_load_dwordx2 v[248:249], v[50:51], off offset:1280
	global_load_dwordx2 v[250:251], v[50:51], off offset:1408
	v_lshlrev_b64 v[48:49], 2, v[196:197]
	v_lshl_add_u64 v[50:51], s[70:71], 0, v[48:49]
	global_load_dwordx4 v[92:95], v[50:51], off
	global_load_dwordx4 v[88:91], v[50:51], off offset:16
	v_lshl_add_u64 v[56:57], s[14:15], 0, v[48:49]
	global_load_dwordx4 v[80:83], v[56:57], off
	global_load_dwordx4 v[76:79], v[56:57], off offset:16
	global_load_dwordx4 v[52:55], v[50:51], off offset:528
	global_load_dwordx4 v[60:63], v[50:51], off offset:512
	s_nop 0
	global_load_dwordx4 v[48:51], v[56:57], off offset:528
	s_nop 0
	global_load_dwordx4 v[56:59], v[56:57], off offset:512
	s_cmp_gt_i32 s2, 1
	s_waitcnt vmcnt(0)
	v_pk_mul_f32 v[206:207], v[206:207], s[16:17] op_sel_hi:[1,0]
	s_nop 0
	v_fma_f32 v199, -v206, v206, v207
	v_max_f32_e32 v199, 0, v199
	v_add_f32_e32 v199, 0x3727c5ac, v199
	v_mul_f32_e32 v208, 0x4f800000, v199
	v_cmp_gt_f32_e32 vcc, s33, v199
	v_xor_b32_e32 v95, 0x80000000, v95
	v_xor_b32_e32 v94, 0x80000000, v94
	v_cndmask_b32_e32 v199, v199, v208, vcc
	v_sqrt_f32_e32 v215, v199
	v_pk_fma_f32 v[208:209], v[88:89], v[206:207], v[168:169] op_sel_hi:[1,0,1] neg_lo:[1,0,0] neg_hi:[1,0,0]
	v_pk_fma_f32 v[168:169], v[94:95], v[206:207], v[174:175] op_sel_hi:[1,0,1]
	v_xor_b32_e32 v91, 0x80000000, v91
	v_add_u32_e32 v174, -1, v215
	v_add_u32_e32 v175, 1, v215
	v_fma_f32 v216, -v174, v215, v199
	v_fma_f32 v217, -v175, v215, v199
	v_cmp_ge_f32_e64 s[0:1], 0, v216
	v_xor_b32_e32 v90, 0x80000000, v90
	v_pk_fma_f32 v[172:173], v[92:93], v[206:207], v[172:173] op_sel_hi:[1,0,1] neg_lo:[1,0,0] neg_hi:[1,0,0]
	v_cndmask_b32_e64 v174, v215, v174, s[0:1]
	v_cmp_lt_f32_e64 s[0:1], 0, v217
	s_nop 1
	v_cndmask_b32_e64 v174, v174, v175, s[0:1]
	v_mul_f32_e32 v175, 0x37800000, v174
	v_cndmask_b32_e32 v174, v174, v175, vcc
	v_cmp_class_f32_e32 vcc, v199, v214
	s_nop 1
	v_cndmask_b32_e32 v199, v174, v199, vcc
	v_div_scale_f32 v215, s[0:1], v199, v199, 1.0
	v_rcp_f32_e32 v216, v215
	v_pk_fma_f32 v[174:175], v[90:91], v[206:207], v[170:171] op_sel_hi:[1,0,1]
	v_div_scale_f32 v170, vcc, 1.0, v199, 1.0
	v_fma_f32 v171, -v215, v216, 1.0
	v_fmac_f32_e32 v216, v171, v216
	v_mul_f32_e32 v171, v170, v216
	v_fma_f32 v207, -v215, v171, v170
	v_fmac_f32_e32 v171, v207, v216
	v_fma_f32 v170, -v215, v171, v170
	v_div_fmas_f32 v170, v170, v216, v171
	v_div_fixup_f32 v170, v170, v199, 1.0
	v_pk_fma_f32 v[168:169], v[168:169], v[170:171], v[82:83] op_sel_hi:[1,0,1]
	v_pk_fma_f32 v[172:173], v[172:173], v[170:171], v[80:81] op_sel_hi:[1,0,1]
	v_pk_fma_f32 v[174:175], v[174:175], v[170:171], v[78:79] op_sel_hi:[1,0,1]
	v_pk_fma_f32 v[208:209], v[208:209], v[170:171], v[76:77] op_sel_hi:[1,0,1]
	s_mov_b64 s[0:1], -1
	s_cbranch_scc0 .LBB0_408
	s_waitcnt lgkmcnt(0)
	v_add_f32_e32 v171, v68, v172
	v_mul_f32_e32 v171, 0xbfb8aa3b, v171
	v_add_f32_e32 v199, v64, v208
	v_exp_f32_e32 v171, v171
	v_mul_f32_e32 v199, 0xbfb8aa3b, v199
	v_exp_f32_e32 v207, v199
	v_add_f32_e32 v215, v65, v209
	v_add_f32_e32 v171, 1.0, v171
	v_rcp_f32_e32 v199, v171
	v_add_f32_e32 v171, 1.0, v207
	v_add_f32_e32 v207, v69, v173
	v_mul_f32_e32 v207, 0xbfb8aa3b, v207
	v_exp_f32_e32 v207, v207
	v_mul_f32_e32 v215, 0xbfb8aa3b, v215
	v_exp_f32_e32 v217, v215
	v_rcp_f32_e32 v215, v171
	v_add_f32_e32 v171, 1.0, v207
	v_add_f32_e32 v207, v70, v168
	v_rcp_f32_e32 v216, v171
	v_add_f32_e32 v171, 1.0, v217
	v_mul_f32_e32 v207, 0xbfb8aa3b, v207
	v_add_f32_e32 v217, v66, v174
	v_exp_f32_e32 v207, v207
	v_mul_f32_e32 v217, 0xbfb8aa3b, v217
	v_exp_f32_e32 v219, v217
	v_rcp_f32_e32 v217, v171
	v_add_f32_e32 v171, 1.0, v207
	v_add_f32_e32 v207, v71, v169
	v_rcp_f32_e32 v218, v171
	v_add_f32_e32 v171, 1.0, v219
	v_mul_f32_e32 v207, 0xbfb8aa3b, v207
	v_add_f32_e32 v219, v67, v175
	v_exp_f32_e32 v207, v207
	v_mul_f32_e32 v219, 0xbfb8aa3b, v219
	v_exp_f32_e32 v220, v219
	v_rcp_f32_e32 v219, v171
	v_add_f32_e32 v171, 1.0, v207
	v_rcp_f32_e32 v221, v171
	v_add_f32_e32 v171, 1.0, v220
	v_rcp_f32_e32 v220, v171
	s_mov_b64 s[0:1], 0

; __device__ __forceinline__ unsigned cvt_pk_bf16(float lo, float hi) { unsigned r; asm volatile("v_cvt_pk_bf16_f32 %0, %1, %2" : "=v"(r) : "v"(lo), "v"(hi)); return r; }
; __device__ __forceinline__ float sigmoidf_(float x) { return __builtin_amdgcn_rcpf(1.0f + __expf(-x)); }
; __device__ __forceinline__ float gelu_tanh(float x) { return x * sigmoidf_(1.5957691216057308f * (x + 0.044715f * x * x * x)); }
; __device__ __forceinline__ f32x2 ln_stats(f32x2 sm) { const float mu = sm[0] * (1.f / D); const float var = fmaxf(sm[1] * (1.f / D) - mu * mu, 0.f); return (f32x2){mu, 1.0f / sqrtf(var + LN_EPS)}; }
;     __device__ __forceinline__ void operator()(const f32x4 (&acc)[2][2][4][2], const Unit& u, int wr, int wc, int fr, int fq) const {
;     ...
;                 for (int m = 0; m < 4; ++m) {
;                     const int r = row0 + ai * HALF + m * 16;
;                     bf16_t* rowp = Z + (size_t)r * NZ + col0;
;                     const f32x2 st = ln_stats(*(const f32x2*)(rsum + 2 * (size_t)r));
; #pragma unroll
;                     for (int bj = 0; bj < 2; ++bj) {
;                         f32x4 v0 = (acc[ai][bj][m][0] - s1[bj][0] * st[0]) * st[1] + s2[bj][0], v1 = (acc[ai][bj][m][1] - s1[bj][1] * st[0]) * st[1] + s2[bj][1];
;                         if (mode == 1) {
; #pragma unroll
;                             for (int j = 0; j < 4; ++j) { v0[j] = gelu_tanh(v0[j]); v1[j] = gelu_tanh(v1[j]); }
;                         } else if (mode == 2) {
; #pragma unroll
;                             for (int j = 0; j < 4; ++j) { v0[j] = sigmoidf_(v0[j] + gb[bj][0][j]); v1[j] = sigmoidf_(v1[j] + gb[bj][1][j]); }
;                         }
;                         u32x4 w; w.x = cvt_pk_bf16(v0[0], v0[1]); w.y = cvt_pk_bf16(v0[2], v0[3]); w.z = cvt_pk_bf16(v1[0], v1[1]); w.w = cvt_pk_bf16(v1[2], v1[3]);
;                         *(u32x4*)(rowp + bj * HALF) = w;
.LBB0_418:
	v_cvt_pk_bf16_f32 v160, v170, v172
	v_cvt_pk_bf16_f32 v161, v174, v206
	v_cvt_pk_bf16_f32 v162, v171, v173
	v_cvt_pk_bf16_f32 v163, v175, v199
	global_store_dwordx4 v[168:169], v[160:163], off offset:256
	s_cmp_gt_i32 s2, 1
	s_nop 0
	v_lshl_add_u64 v[160:161], v[204:205], 3, s[54:55]
	v_mov_b32_e32 v160, v238
	v_mov_b32_e32 v161, v239
	s_nop 0
	v_pk_mul_f32 v[160:161], v[160:161], s[16:17] op_sel_hi:[1,0]
	s_nop 0
	v_fma_f32 v162, -v160, v160, v161
	v_max_f32_e32 v162, 0, v162
	v_add_f32_e32 v162, 0x3727c5ac, v162
	v_mul_f32_e32 v163, 0x4f800000, v162
	v_cmp_gt_f32_e32 vcc, s33, v162
	v_pk_fma_f32 v[158:159], v[94:95], v[160:161], v[158:159] op_sel_hi:[1,0,1]
	v_pk_fma_f32 v[156:157], v[92:93], v[160:161], v[156:157] op_sel_hi:[1,0,1] neg_lo:[1,0,0] neg_hi:[1,0,0]
	v_cndmask_b32_e32 v164, v162, v163, vcc
	v_sqrt_f32_e32 v165, v164
	v_pk_fma_f32 v[162:163], v[90:91], v[160:161], v[154:155] op_sel_hi:[1,0,1]
	v_add_u32_e32 v154, -1, v165
	v_add_u32_e32 v155, 1, v165
	v_fma_f32 v166, -v154, v165, v164
	v_fma_f32 v167, -v155, v165, v164
	v_cmp_ge_f32_e64 s[0:1], 0, v166
	s_nop 1
	v_cndmask_b32_e64 v154, v165, v154, s[0:1]
	v_cmp_lt_f32_e64 s[0:1], 0, v167
	s_nop 1
	v_cndmask_b32_e64 v154, v154, v155, s[0:1]
	v_mul_f32_e32 v155, 0x37800000, v154
	v_cndmask_b32_e32 v154, v154, v155, vcc
	v_cmp_class_f32_e32 vcc, v164, v214
	s_nop 1
	v_cndmask_b32_e32 v154, v154, v164, vcc
	v_div_scale_f32 v155, s[0:1], v154, v154, 1.0
	v_rcp_f32_e32 v166, v155
	v_pk_fma_f32 v[164:165], v[88:89], v[160:161], v[152:153] op_sel_hi:[1,0,1] neg_lo:[1,0,0] neg_hi:[1,0,0]
	v_div_scale_f32 v152, vcc, 1.0, v154, 1.0
	v_fma_f32 v153, -v155, v166, 1.0
	v_fmac_f32_e32 v166, v153, v166
	v_mul_f32_e32 v153, v152, v166
	v_fma_f32 v161, -v155, v153, v152
	v_fmac_f32_e32 v153, v161, v166
	v_fma_f32 v152, -v155, v153, v152
	v_div_fmas_f32 v152, v152, v166, v153
	v_div_fixup_f32 v154, v152, v154, 1.0
	v_pk_fma_f32 v[152:153], v[158:159], v[154:155], v[82:83] op_sel_hi:[1,0,1]
	v_pk_fma_f32 v[156:157], v[156:157], v[154:155], v[80:81] op_sel_hi:[1,0,1]
	v_pk_fma_f32 v[158:159], v[162:163], v[154:155], v[78:79] op_sel_hi:[1,0,1]
	v_pk_fma_f32 v[162:163], v[164:165], v[154:155], v[76:77] op_sel_hi:[1,0,1]
	s_mov_b64 s[0:1], -1
	s_cbranch_scc0 .LBB0_420
	s_waitcnt lgkmcnt(0)
	v_add_f32_e32 v155, v68, v156
	v_mul_f32_e32 v155, 0xbfb8aa3b, v155
	v_add_f32_e32 v161, v64, v162
	v_exp_f32_e32 v155, v155
	v_mul_f32_e32 v161, 0xbfb8aa3b, v161
	v_exp_f32_e32 v161, v161
	v_add_f32_e32 v165, v65, v163
	v_add_f32_e32 v155, 1.0, v155
	v_rcp_f32_e32 v164, v155
	v_add_f32_e32 v155, 1.0, v161
	v_add_f32_e32 v161, v69, v157
	v_mul_f32_e32 v161, 0xbfb8aa3b, v161
	v_exp_f32_e32 v161, v161
	v_mul_f32_e32 v165, 0xbfb8aa3b, v165
	v_exp_f32_e32 v167, v165
	v_rcp_f32_e32 v165, v155
	v_add_f32_e32 v155, 1.0, v161
	v_add_f32_e32 v161, v70, v152
	v_rcp_f32_e32 v166, v155
	v_add_f32_e32 v155, 1.0, v167
	v_mul_f32_e32 v161, 0xbfb8aa3b, v161
	v_add_f32_e32 v167, v66, v158
	v_exp_f32_e32 v161, v161
	v_mul_f32_e32 v167, 0xbfb8aa3b, v167
	v_exp_f32_e32 v169, v167
	v_rcp_f32_e32 v167, v155
	v_add_f32_e32 v155, 1.0, v161
	v_add_f32_e32 v161, v71, v153
	v_rcp_f32_e32 v168, v155
	v_add_f32_e32 v155, 1.0, v169
	v_mul_f32_e32 v161, 0xbfb8aa3b, v161
	v_add_f32_e32 v169, v67, v159
	v_exp_f32_e32 v161, v161
	v_mul_f32_e32 v169, 0xbfb8aa3b, v169
	v_exp_f32_e32 v170, v169
	v_rcp_f32_e32 v169, v155
	v_add_f32_e32 v155, 1.0, v161
	v_rcp_f32_e32 v171, v155
	v_add_f32_e32 v155, 1.0, v170
	v_rcp_f32_e32 v170, v155
	s_mov_b64 s[0:1], 0

; __device__ __forceinline__ unsigned cvt_pk_bf16(float lo, float hi) { unsigned r; asm volatile("v_cvt_pk_bf16_f32 %0, %1, %2" : "=v"(r) : "v"(lo), "v"(hi)); return r; }
; __device__ __forceinline__ float sigmoidf_(float x) { return __builtin_amdgcn_rcpf(1.0f + __expf(-x)); }
; __device__ __forceinline__ float gelu_tanh(float x) { return x * sigmoidf_(1.5957691216057308f * (x + 0.044715f * x * x * x)); }
; __device__ __forceinline__ f32x2 ln_stats(f32x2 sm) { const float mu = sm[0] * (1.f / D); const float var = fmaxf(sm[1] * (1.f / D) - mu * mu, 0.f); return (f32x2){mu, 1.0f / sqrtf(var + LN_EPS)}; }
;     __device__ __forceinline__ void operator()(const f32x4 (&acc)[2][2][4][2], const Unit& u, int wr, int wc, int fr, int fq) const {
;     ...
;                 for (int m = 0; m < 4; ++m) {
;                     const int r = row0 + ai * HALF + m * 16;
;                     bf16_t* rowp = Z + (size_t)r * NZ + col0;
;                     const f32x2 st = ln_stats(*(const f32x2*)(rsum + 2 * (size_t)r));
; #pragma unroll
;                     for (int bj = 0; bj < 2; ++bj) {
;                         f32x4 v0 = (acc[ai][bj][m][0] - s1[bj][0] * st[0]) * st[1] + s2[bj][0], v1 = (acc[ai][bj][m][1] - s1[bj][1] * st[0]) * st[1] + s2[bj][1];
;                         if (mode == 1) {
; #pragma unroll
;                             for (int j = 0; j < 4; ++j) { v0[j] = gelu_tanh(v0[j]); v1[j] = gelu_tanh(v1[j]); }
;                         } else if (mode == 2) {
; #pragma unroll
;                             for (int j = 0; j < 4; ++j) { v0[j] = sigmoidf_(v0[j] + gb[bj][0][j]); v1[j] = sigmoidf_(v1[j] + gb[bj][1][j]); }
;                         }
;                         u32x4 w; w.x = cvt_pk_bf16(v0[0], v0[1]); w.y = cvt_pk_bf16(v0[2], v0[3]); w.z = cvt_pk_bf16(v1[0], v1[1]); w.w = cvt_pk_bf16(v1[2], v1[3]);
;                         *(u32x4*)(rowp + bj * HALF) = w;
.LBB0_430:
	v_cvt_pk_bf16_f32 v144, v154, v156
	v_cvt_pk_bf16_f32 v145, v158, v161
	v_cvt_pk_bf16_f32 v146, v155, v157
	v_cvt_pk_bf16_f32 v147, v159, v160
	global_store_dwordx4 v[152:153], v[144:147], off offset:256
	s_cmp_gt_i32 s2, 1
	s_nop 0
	v_lshl_add_u64 v[144:145], v[202:203], 3, s[54:55]
	v_mov_b32_e32 v144, v240
	v_mov_b32_e32 v145, v241
	s_nop 0
	v_pk_mul_f32 v[144:145], v[144:145], s[16:17] op_sel_hi:[1,0]
	s_nop 0
	v_fma_f32 v146, -v144, v144, v145
	v_max_f32_e32 v146, 0, v146
	v_add_f32_e32 v146, 0x3727c5ac, v146
	v_mul_f32_e32 v147, 0x4f800000, v146
	v_cmp_gt_f32_e32 vcc, s33, v146
	v_pk_fma_f32 v[142:143], v[94:95], v[144:145], v[142:143] op_sel_hi:[1,0,1]
	v_pk_fma_f32 v[140:141], v[92:93], v[144:145], v[140:141] op_sel_hi:[1,0,1] neg_lo:[1,0,0] neg_hi:[1,0,0]
	v_cndmask_b32_e32 v148, v146, v147, vcc
	v_sqrt_f32_e32 v149, v148
	v_pk_fma_f32 v[146:147], v[90:91], v[144:145], v[138:139] op_sel_hi:[1,0,1]
	v_add_u32_e32 v138, -1, v149
	v_add_u32_e32 v139, 1, v149
	v_fma_f32 v150, -v138, v149, v148
	v_fma_f32 v151, -v139, v149, v148
	v_cmp_ge_f32_e64 s[0:1], 0, v150
	s_nop 1
	v_cndmask_b32_e64 v138, v149, v138, s[0:1]
	v_cmp_lt_f32_e64 s[0:1], 0, v151
	s_nop 1
	v_cndmask_b32_e64 v138, v138, v139, s[0:1]
	v_mul_f32_e32 v139, 0x37800000, v138
	v_cndmask_b32_e32 v138, v138, v139, vcc
	v_cmp_class_f32_e32 vcc, v148, v214
	s_nop 1
	v_cndmask_b32_e32 v138, v138, v148, vcc
	v_div_scale_f32 v139, s[0:1], v138, v138, 1.0
	v_rcp_f32_e32 v150, v139
	v_pk_fma_f32 v[148:149], v[88:89], v[144:145], v[136:137] op_sel_hi:[1,0,1] neg_lo:[1,0,0] neg_hi:[1,0,0]
	v_div_scale_f32 v136, vcc, 1.0, v138, 1.0
	v_fma_f32 v137, -v139, v150, 1.0
	v_fmac_f32_e32 v150, v137, v150
	v_mul_f32_e32 v137, v136, v150
	v_fma_f32 v145, -v139, v137, v136
	v_fmac_f32_e32 v137, v145, v150
	v_fma_f32 v136, -v139, v137, v136
	v_div_fmas_f32 v136, v136, v150, v137
	v_div_fixup_f32 v138, v136, v138, 1.0
	v_pk_fma_f32 v[136:137], v[142:143], v[138:139], v[82:83] op_sel_hi:[1,0,1]
	v_pk_fma_f32 v[140:141], v[140:141], v[138:139], v[80:81] op_sel_hi:[1,0,1]
	v_pk_fma_f32 v[142:143], v[146:147], v[138:139], v[78:79] op_sel_hi:[1,0,1]
	v_pk_fma_f32 v[146:147], v[148:149], v[138:139], v[76:77] op_sel_hi:[1,0,1]
	s_mov_b64 s[0:1], -1
	s_cbranch_scc0 .LBB0_432
	s_waitcnt lgkmcnt(0)
	v_add_f32_e32 v139, v68, v140
	v_mul_f32_e32 v139, 0xbfb8aa3b, v139
	v_add_f32_e32 v145, v64, v146
	v_exp_f32_e32 v139, v139
	v_mul_f32_e32 v145, 0xbfb8aa3b, v145
	v_exp_f32_e32 v145, v145
	v_add_f32_e32 v149, v65, v147
	v_add_f32_e32 v139, 1.0, v139
	v_rcp_f32_e32 v148, v139
	v_add_f32_e32 v139, 1.0, v145
	v_add_f32_e32 v145, v69, v141
	v_mul_f32_e32 v145, 0xbfb8aa3b, v145
	v_exp_f32_e32 v145, v145
	v_mul_f32_e32 v149, 0xbfb8aa3b, v149
	v_exp_f32_e32 v151, v149
	v_rcp_f32_e32 v149, v139
	v_add_f32_e32 v139, 1.0, v145
	v_add_f32_e32 v145, v70, v136
	v_rcp_f32_e32 v150, v139
	v_add_f32_e32 v139, 1.0, v151
	v_mul_f32_e32 v145, 0xbfb8aa3b, v145
	v_add_f32_e32 v151, v66, v142
	v_exp_f32_e32 v145, v145
	v_mul_f32_e32 v151, 0xbfb8aa3b, v151
	v_exp_f32_e32 v153, v151
	v_rcp_f32_e32 v151, v139
	v_add_f32_e32 v139, 1.0, v145
	v_add_f32_e32 v145, v71, v137
	v_rcp_f32_e32 v152, v139
	v_add_f32_e32 v139, 1.0, v153
	v_mul_f32_e32 v145, 0xbfb8aa3b, v145
	v_add_f32_e32 v153, v67, v143
	v_exp_f32_e32 v145, v145
	v_mul_f32_e32 v153, 0xbfb8aa3b, v153
	v_exp_f32_e32 v154, v153
	v_rcp_f32_e32 v153, v139
	v_add_f32_e32 v139, 1.0, v145
	v_rcp_f32_e32 v155, v139
	v_add_f32_e32 v139, 1.0, v154
	v_rcp_f32_e32 v154, v139
	s_mov_b64 s[0:1], 0

; __device__ __forceinline__ unsigned cvt_pk_bf16(float lo, float hi) { unsigned r; asm volatile("v_cvt_pk_bf16_f32 %0, %1, %2" : "=v"(r) : "v"(lo), "v"(hi)); return r; }
; __device__ __forceinline__ float sigmoidf_(float x) { return __builtin_amdgcn_rcpf(1.0f + __expf(-x)); }
; __device__ __forceinline__ float gelu_tanh(float x) { return x * sigmoidf_(1.5957691216057308f * (x + 0.044715f * x * x * x)); }
; __device__ __forceinline__ f32x2 ln_stats(f32x2 sm) { const float mu = sm[0] * (1.f / D); const float var = fmaxf(sm[1] * (1.f / D) - mu * mu, 0.f); return (f32x2){mu, 1.0f / sqrtf(var + LN_EPS)}; }
;     __device__ __forceinline__ void operator()(const f32x4 (&acc)[2][2][4][2], const Unit& u, int wr, int wc, int fr, int fq) const {
;     ...
;                 for (int m = 0; m < 4; ++m) {
;                     const int r = row0 + ai * HALF + m * 16;
;                     bf16_t* rowp = Z + (size_t)r * NZ + col0;
;                     const f32x2 st = ln_stats(*(const f32x2*)(rsum + 2 * (size_t)r));
; #pragma unroll
;                     for (int bj = 0; bj < 2; ++bj) {
;                         f32x4 v0 = (acc[ai][bj][m][0] - s1[bj][0] * st[0]) * st[1] + s2[bj][0], v1 = (acc[ai][bj][m][1] - s1[bj][1] * st[0]) * st[1] + s2[bj][1];
;                         if (mode == 1) {
; #pragma unroll
;                             for (int j = 0; j < 4; ++j) { v0[j] = gelu_tanh(v0[j]); v1[j] = gelu_tanh(v1[j]); }
;                         } else if (mode == 2) {
; #pragma unroll
;                             for (int j = 0; j < 4; ++j) { v0[j] = sigmoidf_(v0[j] + gb[bj][0][j]); v1[j] = sigmoidf_(v1[j] + gb[bj][1][j]); }
;                         }
;                         u32x4 w; w.x = cvt_pk_bf16(v0[0], v0[1]); w.y = cvt_pk_bf16(v0[2], v0[3]); w.z = cvt_pk_bf16(v1[0], v1[1]); w.w = cvt_pk_bf16(v1[2], v1[3]);
;                         *(u32x4*)(rowp + bj * HALF) = w;
.LBB0_442:
	v_cvt_pk_bf16_f32 v128, v138, v140
	v_cvt_pk_bf16_f32 v129, v142, v145
	v_cvt_pk_bf16_f32 v130, v139, v141
	v_cvt_pk_bf16_f32 v131, v143, v144
	global_store_dwordx4 v[136:137], v[128:131], off offset:256
	s_cmp_gt_i32 s2, 1
	s_nop 0
	v_lshl_add_u64 v[128:129], v[200:201], 3, s[54:55]
	v_mov_b32_e32 v128, v242
	v_mov_b32_e32 v129, v243
	s_nop 0
	v_pk_mul_f32 v[128:129], v[128:129], s[16:17] op_sel_hi:[1,0]
	s_nop 0
	v_fma_f32 v130, -v128, v128, v129
	v_max_f32_e32 v130, 0, v130
	v_add_f32_e32 v130, 0x3727c5ac, v130
	v_mul_f32_e32 v131, 0x4f800000, v130
	v_cmp_gt_f32_e32 vcc, s33, v130
	v_pk_fma_f32 v[126:127], v[94:95], v[128:129], v[126:127] op_sel_hi:[1,0,1]
	v_pk_fma_f32 v[124:125], v[92:93], v[128:129], v[124:125] op_sel_hi:[1,0,1] neg_lo:[1,0,0] neg_hi:[1,0,0]
	v_cndmask_b32_e32 v132, v130, v131, vcc
	v_sqrt_f32_e32 v133, v132
	v_pk_fma_f32 v[130:131], v[90:91], v[128:129], v[122:123] op_sel_hi:[1,0,1]
	v_add_u32_e32 v122, -1, v133
	v_add_u32_e32 v123, 1, v133
	v_fma_f32 v134, -v122, v133, v132
	v_fma_f32 v135, -v123, v133, v132
	v_cmp_ge_f32_e64 s[0:1], 0, v134
	s_nop 1
	v_cndmask_b32_e64 v122, v133, v122, s[0:1]
	v_cmp_lt_f32_e64 s[0:1], 0, v135
	s_nop 1
	v_cndmask_b32_e64 v122, v122, v123, s[0:1]
	v_mul_f32_e32 v123, 0x37800000, v122
	v_cndmask_b32_e32 v122, v122, v123, vcc
	v_cmp_class_f32_e32 vcc, v132, v214
	s_nop 1
	v_cndmask_b32_e32 v122, v122, v132, vcc
	v_div_scale_f32 v123, s[0:1], v122, v122, 1.0
	v_rcp_f32_e32 v134, v123
	v_pk_fma_f32 v[132:133], v[88:89], v[128:129], v[120:121] op_sel_hi:[1,0,1] neg_lo:[1,0,0] neg_hi:[1,0,0]
	v_div_scale_f32 v120, vcc, 1.0, v122, 1.0
	v_fma_f32 v121, -v123, v134, 1.0
	v_fmac_f32_e32 v134, v121, v134
	v_mul_f32_e32 v121, v120, v134
	v_fma_f32 v129, -v123, v121, v120
	v_fmac_f32_e32 v121, v129, v134
	v_fma_f32 v120, -v123, v121, v120
	v_div_fmas_f32 v120, v120, v134, v121
	v_div_fixup_f32 v122, v120, v122, 1.0
	v_pk_fma_f32 v[120:121], v[126:127], v[122:123], v[82:83] op_sel_hi:[1,0,1]
	v_pk_fma_f32 v[124:125], v[124:125], v[122:123], v[80:81] op_sel_hi:[1,0,1]
	v_pk_fma_f32 v[126:127], v[130:131], v[122:123], v[78:79] op_sel_hi:[1,0,1]
	v_pk_fma_f32 v[130:131], v[132:133], v[122:123], v[76:77] op_sel_hi:[1,0,1]
	s_mov_b64 s[0:1], -1
	s_cbranch_scc0 .LBB0_444
	s_waitcnt lgkmcnt(0)
	v_add_f32_e32 v123, v68, v124
	v_mul_f32_e32 v123, 0xbfb8aa3b, v123
	v_add_f32_e32 v129, v64, v130
	v_exp_f32_e32 v123, v123
	v_mul_f32_e32 v129, 0xbfb8aa3b, v129
	v_exp_f32_e32 v129, v129
	v_add_f32_e32 v133, v65, v131
	v_add_f32_e32 v123, 1.0, v123
	v_rcp_f32_e32 v132, v123
	v_add_f32_e32 v123, 1.0, v129
	v_add_f32_e32 v129, v69, v125
	v_mul_f32_e32 v129, 0xbfb8aa3b, v129
	v_exp_f32_e32 v129, v129
	v_mul_f32_e32 v133, 0xbfb8aa3b, v133
	v_exp_f32_e32 v135, v133
	v_rcp_f32_e32 v133, v123
	v_add_f32_e32 v123, 1.0, v129
	v_add_f32_e32 v129, v70, v120
	v_rcp_f32_e32 v134, v123
	v_add_f32_e32 v123, 1.0, v135
	v_mul_f32_e32 v129, 0xbfb8aa3b, v129
	v_add_f32_e32 v135, v66, v126
	v_exp_f32_e32 v129, v129
	v_mul_f32_e32 v135, 0xbfb8aa3b, v135
	v_exp_f32_e32 v137, v135
	v_rcp_f32_e32 v135, v123
	v_add_f32_e32 v123, 1.0, v129
	v_add_f32_e32 v129, v71, v121
	v_rcp_f32_e32 v136, v123
	v_add_f32_e32 v123, 1.0, v137
	v_mul_f32_e32 v129, 0xbfb8aa3b, v129
	v_add_f32_e32 v137, v67, v127
	v_exp_f32_e32 v129, v129
	v_mul_f32_e32 v137, 0xbfb8aa3b, v137
	v_exp_f32_e32 v138, v137
	v_rcp_f32_e32 v137, v123
	v_add_f32_e32 v123, 1.0, v129
	v_rcp_f32_e32 v139, v123
	v_add_f32_e32 v123, 1.0, v138
	v_rcp_f32_e32 v138, v123
	s_mov_b64 s[0:1], 0

; __device__ __forceinline__ unsigned cvt_pk_bf16(float lo, float hi) { unsigned r; asm volatile("v_cvt_pk_bf16_f32 %0, %1, %2" : "=v"(r) : "v"(lo), "v"(hi)); return r; }
; __device__ __forceinline__ float sigmoidf_(float x) { return __builtin_amdgcn_rcpf(1.0f + __expf(-x)); }
; __device__ __forceinline__ float gelu_tanh(float x) { return x * sigmoidf_(1.5957691216057308f * (x + 0.044715f * x * x * x)); }
; __device__ __forceinline__ f32x2 ln_stats(f32x2 sm) { const float mu = sm[0] * (1.f / D); const float var = fmaxf(sm[1] * (1.f / D) - mu * mu, 0.f); return (f32x2){mu, 1.0f / sqrtf(var + LN_EPS)}; }
;     __device__ __forceinline__ void operator()(const f32x4 (&acc)[2][2][4][2], const Unit& u, int wr, int wc, int fr, int fq) const {
;     ...
;                 for (int m = 0; m < 4; ++m) {
;                     const int r = row0 + ai * HALF + m * 16;
;                     bf16_t* rowp = Z + (size_t)r * NZ + col0;
;                     const f32x2 st = ln_stats(*(const f32x2*)(rsum + 2 * (size_t)r));
; #pragma unroll
;                     for (int bj = 0; bj < 2; ++bj) {
;                         f32x4 v0 = (acc[ai][bj][m][0] - s1[bj][0] * st[0]) * st[1] + s2[bj][0], v1 = (acc[ai][bj][m][1] - s1[bj][1] * st[0]) * st[1] + s2[bj][1];
;                         if (mode == 1) {
; #pragma unroll
;                             for (int j = 0; j < 4; ++j) { v0[j] = gelu_tanh(v0[j]); v1[j] = gelu_tanh(v1[j]); }
;                         } else if (mode == 2) {
; #pragma unroll
;                             for (int j = 0; j < 4; ++j) { v0[j] = sigmoidf_(v0[j] + gb[bj][0][j]); v1[j] = sigmoidf_(v1[j] + gb[bj][1][j]); }
;                         }
;                         u32x4 w; w.x = cvt_pk_bf16(v0[0], v0[1]); w.y = cvt_pk_bf16(v0[2], v0[3]); w.z = cvt_pk_bf16(v1[0], v1[1]); w.w = cvt_pk_bf16(v1[2], v1[3]);
;                         *(u32x4*)(rowp + bj * HALF) = w;
.LBB0_454:
	v_cvt_pk_bf16_f32 v112, v122, v124
	v_cvt_pk_bf16_f32 v113, v126, v129
	v_cvt_pk_bf16_f32 v114, v123, v125
	v_cvt_pk_bf16_f32 v115, v127, v128
	global_store_dwordx4 v[120:121], v[112:115], off offset:256
	s_cmp_gt_i32 s2, 1
	s_nop 0
	v_add_u32_e32 v112, 0x80, v198
	v_ashrrev_i32_e32 v113, 31, v112
	v_lshl_add_u64 v[114:115], v[112:113], 3, s[54:55]
	v_mov_b32_e32 v114, v244
	v_mov_b32_e32 v115, v245
	s_nop 0
	v_pk_mul_f32 v[114:115], v[114:115], s[16:17] op_sel_hi:[1,0]
	s_nop 0
	v_fma_f32 v113, -v114, v114, v115
	v_max_f32_e32 v113, 0, v113
	v_add_f32_e32 v113, 0x3727c5ac, v113
	v_mul_f32_e32 v116, 0x4f800000, v113
	v_cmp_gt_f32_e32 vcc, s33, v113
	v_pk_fma_f32 v[110:111], v[94:95], v[114:115], v[110:111] op_sel_hi:[1,0,1]
	v_pk_fma_f32 v[108:109], v[92:93], v[114:115], v[108:109] op_sel_hi:[1,0,1] neg_lo:[1,0,0] neg_hi:[1,0,0]
	v_cndmask_b32_e32 v113, v113, v116, vcc
	v_sqrt_f32_e32 v118, v113
	v_pk_fma_f32 v[116:117], v[90:91], v[114:115], v[106:107] op_sel_hi:[1,0,1]
	v_add_u32_e32 v106, -1, v118
	v_add_u32_e32 v107, 1, v118
	v_fma_f32 v119, -v106, v118, v113
	v_fma_f32 v120, -v107, v118, v113
	v_cmp_ge_f32_e64 s[0:1], 0, v119
	s_nop 1
	v_cndmask_b32_e64 v106, v118, v106, s[0:1]
	v_cmp_lt_f32_e64 s[0:1], 0, v120
	v_pk_fma_f32 v[118:119], v[88:89], v[114:115], v[104:105] op_sel_hi:[1,0,1] neg_lo:[1,0,0] neg_hi:[1,0,0]
	s_nop 0
	v_cndmask_b32_e64 v106, v106, v107, s[0:1]
	v_mul_f32_e32 v107, 0x37800000, v106
	v_cndmask_b32_e32 v106, v106, v107, vcc
	v_cmp_class_f32_e32 vcc, v113, v214
	s_nop 1
	v_cndmask_b32_e32 v106, v106, v113, vcc
	v_div_scale_f32 v107, s[0:1], v106, v106, 1.0
	v_rcp_f32_e32 v113, v107
	v_div_scale_f32 v104, vcc, 1.0, v106, 1.0
	s_mov_b64 s[0:1], -1
	v_fma_f32 v105, -v107, v113, 1.0
	v_fmac_f32_e32 v113, v105, v113
	v_mul_f32_e32 v105, v104, v113
	v_fma_f32 v115, -v107, v105, v104
	v_fmac_f32_e32 v105, v115, v113
	v_fma_f32 v104, -v107, v105, v104
	v_div_fmas_f32 v104, v104, v113, v105
	v_div_fixup_f32 v106, v104, v106, 1.0
	v_pk_fma_f32 v[104:105], v[110:111], v[106:107], v[82:83] op_sel_hi:[1,0,1]
	v_pk_fma_f32 v[108:109], v[108:109], v[106:107], v[80:81] op_sel_hi:[1,0,1]
	v_pk_fma_f32 v[110:111], v[116:117], v[106:107], v[78:79] op_sel_hi:[1,0,1]
	v_pk_fma_f32 v[116:117], v[118:119], v[106:107], v[76:77] op_sel_hi:[1,0,1]
	s_cbranch_scc0 .LBB0_456
	s_waitcnt lgkmcnt(0)
	v_add_f32_e32 v107, v68, v108
	v_mul_f32_e32 v107, 0xbfb8aa3b, v107
	v_add_f32_e32 v113, v64, v116
	v_exp_f32_e32 v107, v107
	v_mul_f32_e32 v113, 0xbfb8aa3b, v113
	v_exp_f32_e32 v115, v113
	v_add_f32_e32 v118, v65, v117
	v_add_f32_e32 v107, 1.0, v107
	v_rcp_f32_e32 v113, v107
	v_add_f32_e32 v107, 1.0, v115
	v_add_f32_e32 v115, v69, v109
	v_mul_f32_e32 v115, 0xbfb8aa3b, v115
	v_exp_f32_e32 v115, v115
	v_mul_f32_e32 v118, 0xbfb8aa3b, v118
	v_exp_f32_e32 v120, v118
	v_rcp_f32_e32 v118, v107
	v_add_f32_e32 v107, 1.0, v115
	v_add_f32_e32 v115, v70, v104
	v_rcp_f32_e32 v119, v107
	v_add_f32_e32 v107, 1.0, v120
	v_mul_f32_e32 v115, 0xbfb8aa3b, v115
	v_add_f32_e32 v120, v66, v110
	v_exp_f32_e32 v115, v115
	v_mul_f32_e32 v120, 0xbfb8aa3b, v120
	v_exp_f32_e32 v122, v120
	v_rcp_f32_e32 v120, v107
	v_add_f32_e32 v107, 1.0, v115
	v_add_f32_e32 v115, v71, v105
	v_rcp_f32_e32 v121, v107
	v_add_f32_e32 v107, 1.0, v122
	v_mul_f32_e32 v115, 0xbfb8aa3b, v115
	v_add_f32_e32 v122, v67, v111
	v_exp_f32_e32 v115, v115
	v_mul_f32_e32 v122, 0xbfb8aa3b, v122
	v_exp_f32_e32 v123, v122
	v_rcp_f32_e32 v122, v107
	v_add_f32_e32 v107, 1.0, v115
	v_rcp_f32_e32 v124, v107
	v_add_f32_e32 v107, 1.0, v123
	v_rcp_f32_e32 v123, v107
	s_mov_b64 s[0:1], 0

; __device__ __forceinline__ unsigned cvt_pk_bf16(float lo, float hi) { unsigned r; asm volatile("v_cvt_pk_bf16_f32 %0, %1, %2" : "=v"(r) : "v"(lo), "v"(hi)); return r; }
; __device__ __forceinline__ float sigmoidf_(float x) { return __builtin_amdgcn_rcpf(1.0f + __expf(-x)); }
; __device__ __forceinline__ float gelu_tanh(float x) { return x * sigmoidf_(1.5957691216057308f * (x + 0.044715f * x * x * x)); }
; __device__ __forceinline__ f32x2 ln_stats(f32x2 sm) { const float mu = sm[0] * (1.f / D); const float var = fmaxf(sm[1] * (1.f / D) - mu * mu, 0.f); return (f32x2){mu, 1.0f / sqrtf(var + LN_EPS)}; }
;     __device__ __forceinline__ void operator()(const f32x4 (&acc)[2][2][4][2], const Unit& u, int wr, int wc, int fr, int fq) const {
;     ...
;                 for (int m = 0; m < 4; ++m) {
;                     const int r = row0 + ai * HALF + m * 16;
;                     bf16_t* rowp = Z + (size_t)r * NZ + col0;
;                     const f32x2 st = ln_stats(*(const f32x2*)(rsum + 2 * (size_t)r));
; #pragma unroll
;                     for (int bj = 0; bj < 2; ++bj) {
;                         f32x4 v0 = (acc[ai][bj][m][0] - s1[bj][0] * st[0]) * st[1] + s2[bj][0], v1 = (acc[ai][bj][m][1] - s1[bj][1] * st[0]) * st[1] + s2[bj][1];
;                         if (mode == 1) {
; #pragma unroll
;                             for (int j = 0; j < 4; ++j) { v0[j] = gelu_tanh(v0[j]); v1[j] = gelu_tanh(v1[j]); }
;                         } else if (mode == 2) {
; #pragma unroll
;                             for (int j = 0; j < 4; ++j) { v0[j] = sigmoidf_(v0[j] + gb[bj][0][j]); v1[j] = sigmoidf_(v1[j] + gb[bj][1][j]); }
;                         }
;                         u32x4 w; w.x = cvt_pk_bf16(v0[0], v0[1]); w.y = cvt_pk_bf16(v0[2], v0[3]); w.z = cvt_pk_bf16(v1[0], v1[1]); w.w = cvt_pk_bf16(v1[2], v1[3]);
;                         *(u32x4*)(rowp + bj * HALF) = w;
.LBB0_466:
	v_cvt_pk_bf16_f32 v96, v106, v108
	v_cvt_pk_bf16_f32 v97, v110, v113
	v_cvt_pk_bf16_f32 v98, v107, v109
	v_cvt_pk_bf16_f32 v99, v111, v112
	global_store_dwordx4 v[104:105], v[96:99], off offset:256
	s_cmp_gt_i32 s2, 1
	s_nop 0
	v_add_u32_e32 v96, 0x90, v198
	v_ashrrev_i32_e32 v97, 31, v96
	v_lshl_add_u64 v[98:99], v[96:97], 3, s[54:55]
	v_mov_b32_e32 v98, v246
	v_mov_b32_e32 v99, v247
	s_nop 0
	v_pk_mul_f32 v[98:99], v[98:99], s[16:17] op_sel_hi:[1,0]
	s_nop 0
	v_fma_f32 v97, -v98, v98, v99
	v_max_f32_e32 v97, 0, v97
	v_add_f32_e32 v97, 0x3727c5ac, v97
	v_mul_f32_e32 v100, 0x4f800000, v97
	v_cmp_gt_f32_e32 vcc, s33, v97
	v_pk_fma_f32 v[86:87], v[94:95], v[98:99], v[86:87] op_sel_hi:[1,0,1]
	v_pk_fma_f32 v[84:85], v[92:93], v[98:99], v[84:85] op_sel_hi:[1,0,1] neg_lo:[1,0,0] neg_hi:[1,0,0]
	v_cndmask_b32_e32 v97, v97, v100, vcc
	v_sqrt_f32_e32 v102, v97
	v_pk_fma_f32 v[100:101], v[90:91], v[98:99], v[74:75] op_sel_hi:[1,0,1]
	v_add_u32_e32 v74, -1, v102
	v_add_u32_e32 v75, 1, v102
	v_fma_f32 v103, -v74, v102, v97
	v_fma_f32 v104, -v75, v102, v97
	v_cmp_ge_f32_e64 s[0:1], 0, v103
	s_nop 1
	v_cndmask_b32_e64 v74, v102, v74, s[0:1]
	v_cmp_lt_f32_e64 s[0:1], 0, v104
	v_pk_fma_f32 v[102:103], v[88:89], v[98:99], v[72:73] op_sel_hi:[1,0,1] neg_lo:[1,0,0] neg_hi:[1,0,0]
	s_nop 0
	v_cndmask_b32_e64 v74, v74, v75, s[0:1]
	v_mul_f32_e32 v75, 0x37800000, v74
	v_cndmask_b32_e32 v74, v74, v75, vcc
	v_cmp_class_f32_e32 vcc, v97, v214
	s_nop 1
	v_cndmask_b32_e32 v74, v74, v97, vcc
	v_div_scale_f32 v75, s[0:1], v74, v74, 1.0
	v_rcp_f32_e32 v97, v75
	v_div_scale_f32 v72, vcc, 1.0, v74, 1.0
	s_mov_b64 s[0:1], -1
	v_fma_f32 v73, -v75, v97, 1.0
	v_fmac_f32_e32 v97, v73, v97
	v_mul_f32_e32 v73, v72, v97
	v_fma_f32 v99, -v75, v73, v72
	v_fmac_f32_e32 v73, v99, v97
	v_fma_f32 v72, -v75, v73, v72
	v_div_fmas_f32 v72, v72, v97, v73
	v_div_fixup_f32 v74, v72, v74, 1.0
	v_pk_fma_f32 v[72:73], v[86:87], v[74:75], v[82:83] op_sel_hi:[1,0,1]
	v_pk_fma_f32 v[84:85], v[84:85], v[74:75], v[80:81] op_sel_hi:[1,0,1]
	v_pk_fma_f32 v[86:87], v[100:101], v[74:75], v[78:79] op_sel_hi:[1,0,1]
	v_pk_fma_f32 v[100:101], v[102:103], v[74:75], v[76:77] op_sel_hi:[1,0,1]
	s_cbranch_scc0 .LBB0_468
	s_waitcnt lgkmcnt(0)
	v_add_f32_e32 v75, v68, v84
	v_mul_f32_e32 v75, 0xbfb8aa3b, v75
	v_add_f32_e32 v97, v64, v100
	v_exp_f32_e32 v75, v75
	v_mul_f32_e32 v97, 0xbfb8aa3b, v97
	v_exp_f32_e32 v99, v97
	v_add_f32_e32 v102, v65, v101
	v_add_f32_e32 v75, 1.0, v75
	v_rcp_f32_e32 v97, v75
	v_add_f32_e32 v75, 1.0, v99
	v_add_f32_e32 v99, v69, v85
	v_mul_f32_e32 v99, 0xbfb8aa3b, v99
	v_exp_f32_e32 v99, v99
	v_mul_f32_e32 v102, 0xbfb8aa3b, v102
	v_exp_f32_e32 v104, v102
	v_rcp_f32_e32 v102, v75
	v_add_f32_e32 v75, 1.0, v99
	v_add_f32_e32 v99, v70, v72
	v_rcp_f32_e32 v103, v75
	v_add_f32_e32 v75, 1.0, v104
	v_mul_f32_e32 v99, 0xbfb8aa3b, v99
	v_add_f32_e32 v104, v66, v86
	v_exp_f32_e32 v99, v99
	v_mul_f32_e32 v104, 0xbfb8aa3b, v104
	v_exp_f32_e32 v106, v104
	v_rcp_f32_e32 v104, v75
	v_add_f32_e32 v75, 1.0, v99
	v_add_f32_e32 v99, v71, v73
	v_rcp_f32_e32 v105, v75
	v_add_f32_e32 v75, 1.0, v106
	v_mul_f32_e32 v99, 0xbfb8aa3b, v99
	v_add_f32_e32 v106, v67, v87
	v_exp_f32_e32 v99, v99
	v_mul_f32_e32 v106, 0xbfb8aa3b, v106
	v_exp_f32_e32 v107, v106
	v_rcp_f32_e32 v106, v75
	v_add_f32_e32 v75, 1.0, v99
	v_rcp_f32_e32 v108, v75
	v_add_f32_e32 v75, 1.0, v107
	v_rcp_f32_e32 v107, v75
	s_mov_b64 s[0:1], 0

; __device__ __forceinline__ unsigned cvt_pk_bf16(float lo, float hi) { unsigned r; asm volatile("v_cvt_pk_bf16_f32 %0, %1, %2" : "=v"(r) : "v"(lo), "v"(hi)); return r; }
; __device__ __forceinline__ float sigmoidf_(float x) { return __builtin_amdgcn_rcpf(1.0f + __expf(-x)); }
; __device__ __forceinline__ float gelu_tanh(float x) { return x * sigmoidf_(1.5957691216057308f * (x + 0.044715f * x * x * x)); }
; __device__ __forceinline__ f32x2 ln_stats(f32x2 sm) { const float mu = sm[0] * (1.f / D); const float var = fmaxf(sm[1] * (1.f / D) - mu * mu, 0.f); return (f32x2){mu, 1.0f / sqrtf(var + LN_EPS)}; }
;     __device__ __forceinline__ void operator()(const f32x4 (&acc)[2][2][4][2], const Unit& u, int wr, int wc, int fr, int fq) const {
;     ...
;                 for (int m = 0; m < 4; ++m) {
;                     const int r = row0 + ai * HALF + m * 16;
;                     bf16_t* rowp = Z + (size_t)r * NZ + col0;
;                     const f32x2 st = ln_stats(*(const f32x2*)(rsum + 2 * (size_t)r));
; #pragma unroll
;                     for (int bj = 0; bj < 2; ++bj) {
;                         f32x4 v0 = (acc[ai][bj][m][0] - s1[bj][0] * st[0]) * st[1] + s2[bj][0], v1 = (acc[ai][bj][m][1] - s1[bj][1] * st[0]) * st[1] + s2[bj][1];
;                         if (mode == 1) {
; #pragma unroll
;                             for (int j = 0; j < 4; ++j) { v0[j] = gelu_tanh(v0[j]); v1[j] = gelu_tanh(v1[j]); }
;                         } else if (mode == 2) {
; #pragma unroll
;                             for (int j = 0; j < 4; ++j) { v0[j] = sigmoidf_(v0[j] + gb[bj][0][j]); v1[j] = sigmoidf_(v1[j] + gb[bj][1][j]); }
;                         }
;                         u32x4 w; w.x = cvt_pk_bf16(v0[0], v0[1]); w.y = cvt_pk_bf16(v0[2], v0[3]); w.z = cvt_pk_bf16(v1[0], v1[1]); w.w = cvt_pk_bf16(v1[2], v1[3]);
;                         *(u32x4*)(rowp + bj * HALF) = w;
.LBB0_478:
	v_cvt_pk_bf16_f32 v40, v74, v84
	v_cvt_pk_bf16_f32 v41, v86, v97
	v_cvt_pk_bf16_f32 v42, v75, v85
	v_cvt_pk_bf16_f32 v43, v87, v96
	global_store_dwordx4 v[72:73], v[40:43], off offset:256
	s_cmp_gt_i32 s2, 1
	s_nop 0
	v_add_u32_e32 v40, 0xa0, v198
	v_ashrrev_i32_e32 v41, 31, v40
	v_lshl_add_u64 v[42:43], v[40:41], 3, s[54:55]
	v_mov_b32_e32 v42, v248
	v_mov_b32_e32 v43, v249
	s_nop 0
	v_pk_mul_f32 v[42:43], v[42:43], s[16:17] op_sel_hi:[1,0]
	s_nop 0
	v_fma_f32 v41, -v42, v42, v43
	v_max_f32_e32 v41, 0, v41
	v_add_f32_e32 v41, 0x3727c5ac, v41
	v_mul_f32_e32 v44, 0x4f800000, v41
	v_cmp_gt_f32_e32 vcc, s33, v41
	v_pk_fma_f32 v[30:31], v[94:95], v[42:43], v[30:31] op_sel_hi:[1,0,1]
	v_pk_fma_f32 v[28:29], v[92:93], v[42:43], v[28:29] op_sel_hi:[1,0,1] neg_lo:[1,0,0] neg_hi:[1,0,0]
	v_cndmask_b32_e32 v41, v41, v44, vcc
	v_sqrt_f32_e32 v46, v41
	v_pk_fma_f32 v[44:45], v[90:91], v[42:43], v[26:27] op_sel_hi:[1,0,1]
	v_add_u32_e32 v26, -1, v46
	v_add_u32_e32 v27, 1, v46
	v_fma_f32 v47, -v26, v46, v41
	v_fma_f32 v72, -v27, v46, v41
	v_cmp_ge_f32_e64 s[0:1], 0, v47
	s_nop 1
	v_cndmask_b32_e64 v26, v46, v26, s[0:1]
	v_cmp_lt_f32_e64 s[0:1], 0, v72
	v_pk_fma_f32 v[46:47], v[88:89], v[42:43], v[24:25] op_sel_hi:[1,0,1] neg_lo:[1,0,0] neg_hi:[1,0,0]
	s_nop 0
	v_cndmask_b32_e64 v26, v26, v27, s[0:1]
	v_mul_f32_e32 v27, 0x37800000, v26
	v_cndmask_b32_e32 v26, v26, v27, vcc
	v_cmp_class_f32_e32 vcc, v41, v214
	s_nop 1
	v_cndmask_b32_e32 v26, v26, v41, vcc
	v_div_scale_f32 v27, s[0:1], v26, v26, 1.0
	v_rcp_f32_e32 v41, v27
	v_div_scale_f32 v24, vcc, 1.0, v26, 1.0
	s_mov_b64 s[0:1], -1
	v_fma_f32 v25, -v27, v41, 1.0
	v_fmac_f32_e32 v41, v25, v41
	v_mul_f32_e32 v25, v24, v41
	v_fma_f32 v43, -v27, v25, v24
	v_fmac_f32_e32 v25, v43, v41
	v_fma_f32 v24, -v27, v25, v24
	v_div_fmas_f32 v24, v24, v41, v25
	v_div_fixup_f32 v26, v24, v26, 1.0
	v_pk_fma_f32 v[24:25], v[30:31], v[26:27], v[82:83] op_sel_hi:[1,0,1]
	v_pk_fma_f32 v[28:29], v[28:29], v[26:27], v[80:81] op_sel_hi:[1,0,1]
	v_pk_fma_f32 v[30:31], v[44:45], v[26:27], v[78:79] op_sel_hi:[1,0,1]
	v_pk_fma_f32 v[44:45], v[46:47], v[26:27], v[76:77] op_sel_hi:[1,0,1]
	s_cbranch_scc0 .LBB0_480
	s_waitcnt lgkmcnt(0)
	v_add_f32_e32 v27, v68, v28
	v_mul_f32_e32 v27, 0xbfb8aa3b, v27
	v_add_f32_e32 v41, v64, v44
	v_exp_f32_e32 v27, v27
	v_mul_f32_e32 v41, 0xbfb8aa3b, v41
	v_exp_f32_e32 v43, v41
	v_add_f32_e32 v46, v65, v45
	v_add_f32_e32 v27, 1.0, v27
	v_rcp_f32_e32 v41, v27
	v_add_f32_e32 v27, 1.0, v43
	v_add_f32_e32 v43, v69, v29
	v_mul_f32_e32 v43, 0xbfb8aa3b, v43
	v_exp_f32_e32 v43, v43
	v_mul_f32_e32 v46, 0xbfb8aa3b, v46
	v_exp_f32_e32 v72, v46
	v_rcp_f32_e32 v46, v27
	v_add_f32_e32 v27, 1.0, v43
	v_add_f32_e32 v43, v70, v24
	v_rcp_f32_e32 v47, v27
	v_add_f32_e32 v27, 1.0, v72
	v_mul_f32_e32 v43, 0xbfb8aa3b, v43
	v_add_f32_e32 v72, v66, v30
	v_exp_f32_e32 v43, v43
	v_mul_f32_e32 v72, 0xbfb8aa3b, v72
	v_exp_f32_e32 v74, v72
	v_rcp_f32_e32 v72, v27
	v_add_f32_e32 v27, 1.0, v43
	v_add_f32_e32 v43, v71, v25
	v_rcp_f32_e32 v73, v27
	v_add_f32_e32 v27, 1.0, v74
	v_mul_f32_e32 v43, 0xbfb8aa3b, v43
	v_add_f32_e32 v74, v67, v31
	v_exp_f32_e32 v43, v43
	v_mul_f32_e32 v74, 0xbfb8aa3b, v74
	v_exp_f32_e32 v75, v74
	v_rcp_f32_e32 v74, v27
	v_add_f32_e32 v27, 1.0, v43
	v_rcp_f32_e32 v84, v27
	v_add_f32_e32 v27, 1.0, v75
	v_rcp_f32_e32 v75, v27
	s_mov_b64 s[0:1], 0

; __device__ __forceinline__ unsigned cvt_pk_bf16(float lo, float hi) { unsigned r; asm volatile("v_cvt_pk_bf16_f32 %0, %1, %2" : "=v"(r) : "v"(lo), "v"(hi)); return r; }
; __device__ __forceinline__ float sigmoidf_(float x) { return __builtin_amdgcn_rcpf(1.0f + __expf(-x)); }
; __device__ __forceinline__ float gelu_tanh(float x) { return x * sigmoidf_(1.5957691216057308f * (x + 0.044715f * x * x * x)); }
; __device__ __forceinline__ f32x2 ln_stats(f32x2 sm) { const float mu = sm[0] * (1.f / D); const float var = fmaxf(sm[1] * (1.f / D) - mu * mu, 0.f); return (f32x2){mu, 1.0f / sqrtf(var + LN_EPS)}; }
;     __device__ __forceinline__ void operator()(const f32x4 (&acc)[2][2][4][2], const Unit& u, int wr, int wc, int fr, int fq) const {
;     ...
;                 for (int m = 0; m < 4; ++m) {
;                     const int r = row0 + ai * HALF + m * 16;
;                     bf16_t* rowp = Z + (size_t)r * NZ + col0;
;                     const f32x2 st = ln_stats(*(const f32x2*)(rsum + 2 * (size_t)r));
; #pragma unroll
;                     for (int bj = 0; bj < 2; ++bj) {
;                         f32x4 v0 = (acc[ai][bj][m][0] - s1[bj][0] * st[0]) * st[1] + s2[bj][0], v1 = (acc[ai][bj][m][1] - s1[bj][1] * st[0]) * st[1] + s2[bj][1];
;                         if (mode == 1) {
; #pragma unroll
;                             for (int j = 0; j < 4; ++j) { v0[j] = gelu_tanh(v0[j]); v1[j] = gelu_tanh(v1[j]); }
;                         } else if (mode == 2) {
; #pragma unroll
;                             for (int j = 0; j < 4; ++j) { v0[j] = sigmoidf_(v0[j] + gb[bj][0][j]); v1[j] = sigmoidf_(v1[j] + gb[bj][1][j]); }
;                         }
;                         u32x4 w; w.x = cvt_pk_bf16(v0[0], v0[1]); w.y = cvt_pk_bf16(v0[2], v0[3]); w.z = cvt_pk_bf16(v1[0], v1[1]); w.w = cvt_pk_bf16(v1[2], v1[3]);
;                         *(u32x4*)(rowp + bj * HALF) = w;
.LBB0_490:
	v_cvt_pk_bf16_f32 v16, v26, v28
	v_cvt_pk_bf16_f32 v17, v30, v41
	v_cvt_pk_bf16_f32 v18, v27, v29
	v_cvt_pk_bf16_f32 v19, v31, v40
	global_store_dwordx4 v[24:25], v[16:19], off offset:256
	s_cmp_gt_i32 s2, 1
	s_nop 0
	v_add_u32_e32 v16, 0xb0, v198
	v_ashrrev_i32_e32 v17, 31, v16
	v_lshl_add_u64 v[18:19], v[16:17], 3, s[54:55]
	v_mov_b32_e32 v18, v250
	v_mov_b32_e32 v19, v251
	s_nop 0
	v_pk_mul_f32 v[18:19], v[18:19], s[16:17] op_sel_hi:[1,0]
	s_nop 0
	v_fma_f32 v17, -v18, v18, v19
	v_max_f32_e32 v17, 0, v17
	v_add_f32_e32 v17, 0x3727c5ac, v17
	v_mul_f32_e32 v20, 0x4f800000, v17
	v_cmp_gt_f32_e32 vcc, s33, v17
	v_pk_fma_f32 v[14:15], v[94:95], v[18:19], v[14:15] op_sel_hi:[1,0,1]
	v_pk_fma_f32 v[12:13], v[92:93], v[18:19], v[12:13] op_sel_hi:[1,0,1] neg_lo:[1,0,0] neg_hi:[1,0,0]
	v_cndmask_b32_e32 v17, v17, v20, vcc
	v_sqrt_f32_e32 v22, v17
	v_pk_fma_f32 v[20:21], v[90:91], v[18:19], v[10:11] op_sel_hi:[1,0,1]
	v_add_u32_e32 v10, -1, v22
	v_add_u32_e32 v11, 1, v22
	v_fma_f32 v23, -v10, v22, v17
	v_fma_f32 v24, -v11, v22, v17
	v_cmp_ge_f32_e64 s[0:1], 0, v23
	s_nop 1
	v_cndmask_b32_e64 v10, v22, v10, s[0:1]
	v_cmp_lt_f32_e64 s[0:1], 0, v24
	v_pk_fma_f32 v[22:23], v[88:89], v[18:19], v[8:9] op_sel_hi:[1,0,1] neg_lo:[1,0,0] neg_hi:[1,0,0]
	s_nop 0
	v_cndmask_b32_e64 v10, v10, v11, s[0:1]
	v_mul_f32_e32 v11, 0x37800000, v10
	v_cndmask_b32_e32 v10, v10, v11, vcc
	v_cmp_class_f32_e32 vcc, v17, v214
	s_nop 1
	v_cndmask_b32_e32 v10, v10, v17, vcc
	v_div_scale_f32 v11, s[0:1], v10, v10, 1.0
	v_rcp_f32_e32 v17, v11
	v_div_scale_f32 v8, vcc, 1.0, v10, 1.0
	s_mov_b64 s[0:1], -1
	v_fma_f32 v9, -v11, v17, 1.0
	v_fmac_f32_e32 v17, v9, v17
	v_mul_f32_e32 v9, v8, v17
	v_fma_f32 v19, -v11, v9, v8
	v_fmac_f32_e32 v9, v19, v17
	v_fma_f32 v8, -v11, v9, v8
	v_div_fmas_f32 v8, v8, v17, v9
	v_div_fixup_f32 v10, v8, v10, 1.0
	v_pk_fma_f32 v[8:9], v[14:15], v[10:11], v[82:83] op_sel_hi:[1,0,1]
	v_pk_fma_f32 v[12:13], v[12:13], v[10:11], v[80:81] op_sel_hi:[1,0,1]
	v_pk_fma_f32 v[14:15], v[20:21], v[10:11], v[78:79] op_sel_hi:[1,0,1]
	v_pk_fma_f32 v[20:21], v[22:23], v[10:11], v[76:77] op_sel_hi:[1,0,1]
	s_cbranch_scc0 .LBB0_492
	s_waitcnt lgkmcnt(0)
	v_add_f32_e32 v11, v68, v12
	v_mul_f32_e32 v11, 0xbfb8aa3b, v11
	v_add_f32_e32 v17, v64, v20
	v_exp_f32_e32 v11, v11
	v_mul_f32_e32 v17, 0xbfb8aa3b, v17
	v_exp_f32_e32 v19, v17
	v_add_f32_e32 v22, v65, v21
	v_add_f32_e32 v11, 1.0, v11
	v_rcp_f32_e32 v17, v11
	v_add_f32_e32 v11, 1.0, v19
	v_add_f32_e32 v19, v69, v13
	v_mul_f32_e32 v19, 0xbfb8aa3b, v19
	v_exp_f32_e32 v19, v19
	v_mul_f32_e32 v22, 0xbfb8aa3b, v22
	v_exp_f32_e32 v24, v22
	v_rcp_f32_e32 v22, v11
	v_add_f32_e32 v11, 1.0, v19
	v_add_f32_e32 v19, v70, v8
	v_rcp_f32_e32 v23, v11
	v_add_f32_e32 v11, 1.0, v24
	v_mul_f32_e32 v19, 0xbfb8aa3b, v19
	v_add_f32_e32 v24, v66, v14
	v_exp_f32_e32 v19, v19
	v_mul_f32_e32 v24, 0xbfb8aa3b, v24
	v_exp_f32_e32 v26, v24
	v_rcp_f32_e32 v24, v11
	v_add_f32_e32 v11, 1.0, v19
	v_add_f32_e32 v19, v71, v9
	v_rcp_f32_e32 v25, v11
	v_add_f32_e32 v11, 1.0, v26
	v_mul_f32_e32 v19, 0xbfb8aa3b, v19
	v_add_f32_e32 v26, v67, v15
	v_exp_f32_e32 v19, v19
	v_mul_f32_e32 v26, 0xbfb8aa3b, v26
	v_exp_f32_e32 v27, v26
	v_rcp_f32_e32 v26, v11
	v_add_f32_e32 v11, 1.0, v19
	v_rcp_f32_e32 v28, v11
	v_add_f32_e32 v11, 1.0, v27
	v_rcp_f32_e32 v27, v11
	s_mov_b64 s[0:1], 0

; __device__ __forceinline__ unsigned cvt_pk_bf16(float lo, float hi) { unsigned r; asm volatile("v_cvt_pk_bf16_f32 %0, %1, %2" : "=v"(r) : "v"(lo), "v"(hi)); return r; }
; __device__ __forceinline__ float siluf_(float x) { return x * sigmoidf_(x); }
; __device__ __forceinline__ f32x2 ln_stats(f32x2 sm) { const float mu = sm[0] * (1.f / D); const float var = fmaxf(sm[1] * (1.f / D) - mu * mu, 0.f); return (f32x2){mu, 1.0f / sqrtf(var + LN_EPS)}; }
;     __device__ __forceinline__ void operator()(const f32x4 (&acc)[2][2][4][2], const Unit& u, int wr, int wc, int fr, int fq) const {
;         const int row0 = u.pm * BM + wr * 64 + fr, col0 = u.pn * HALF + wc * 32 + 8 * fq;
;         f32x4 s1[2][2], s2[2][2];
; #pragma unroll
;         for (int bj = 0; bj < 2; ++bj)
; #pragma unroll
;             for (int n = 0; n < 2; ++n) { s1[bj][n] = (f32x4){0.f, 0.f, 0.f, 0.f}; s2[bj][n] = s1[bj][n];
;                 if (rsum) { const int ci = u.pn * BM + bj * HALF + wc * 32 + 8 * fq + 4 * n; s1[bj][n] = *(const f32x4*)(cs + ci); s2[bj][n] = *(const f32x4*)(cs + NZ + ci); } }
; #pragma unroll
;         for (int ai = 0; ai < 2; ++ai)
; #pragma unroll
;             for (int m = 0; m < 4; ++m) {
;                 const int r = row0 + ai * HALF + m * 16;
;                 bf16_t* rowp = H + (size_t)r * ldh + col0;
;                 f32x2 st = (f32x2){0.f, 1.f};
;                 if (rsum) st = ln_stats(*(const f32x2*)(rsum + 2 * (size_t)r));
;                 f32x4 v0, v1;
; #pragma unroll
;                 for (int j = 0; j < 4; ++j) {
;                     const float g0 = st[1] * (acc[ai][0][m][0][j] - st[0] * s1[0][0][j]) + s2[0][0][j], u0 = st[1] * (acc[ai][1][m][0][j] - st[0] * s1[1][0][j]) + s2[1][0][j];
;                     const float g1 = st[1] * (acc[ai][0][m][1][j] - st[0] * s1[0][1][j]) + s2[0][1][j], u1 = st[1] * (acc[ai][1][m][1][j] - st[0] * s1[1][1][j]) + s2[1][1][j];
;                     v0[j] = siluf_(g0) * u0; v1[j] = siluf_(g1) * u1;
;                 }
;                 u32x4 w; w.x = cvt_pk_bf16(v0[0], v0[1]); w.y = cvt_pk_bf16(v0[2], v0[3]); w.z = cvt_pk_bf16(v1[0], v1[1]); w.w = cvt_pk_bf16(v1[2], v1[3]);
;                 *(u32x4*)rowp = w;
.LBB0_1040:
	v_lshl_or_b32 v144, s1, 8, v182
	v_lshl_add_u32 v162, s0, 8, v177
	v_ashrrev_i32_e32 v145, 31, v144
	v_lshlrev_b64 v[64:65], 2, v[144:145]
	v_ashrrev_i32_e32 v163, 31, v162
	v_lshl_add_u64 v[68:69], s[18:19], 0, v[64:65]
	v_lshl_add_u64 v[70:71], s[12:13], 0, v[64:65]
	v_lshl_add_u64 v[64:65], v[162:163], 3, s[8:9]
	global_load_dwordx2 v[164:165], v[64:65], off
	global_load_dwordx2 v[238:239], v[64:65], off offset:128
	global_load_dwordx2 v[240:241], v[64:65], off offset:256
	global_load_dwordx2 v[242:243], v[64:65], off offset:384
	global_load_dwordx2 v[244:245], v[64:65], off offset:1024
	global_load_dwordx2 v[246:247], v[64:65], off offset:1152
	global_load_dwordx2 v[248:249], v[64:65], off offset:1280
	global_load_dwordx2 v[250:251], v[64:65], off offset:1408
	s_nop 0
	global_load_dwordx4 v[64:67], v[70:71], off offset:16
	global_load_dwordx4 v[76:79], v[70:71], off
	global_load_dwordx4 v[72:75], v[68:69], off
	s_nop 0
	global_load_dwordx4 v[68:71], v[68:69], off offset:16
	v_or_b32_e32 v144, 0x80, v144
	v_ashrrev_i32_e32 v145, 31, v144
	v_lshlrev_b64 v[144:145], 2, v[144:145]
	v_lshl_add_u64 v[146:147], s[18:19], 0, v[144:145]
	v_lshl_add_u64 v[144:145], s[12:13], 0, v[144:145]
	global_load_dwordx4 v[188:191], v[144:145], off
	global_load_dwordx4 v[192:195], v[146:147], off
	global_load_dwordx4 v[196:199], v[144:145], off offset:16
	s_nop 0
	global_load_dwordx4 v[144:147], v[146:147], off offset:16
	v_lshl_or_b32 v166, s1, 7, v182
	v_mov_b64_e32 v[160:161], s[40:41]
	v_ashrrev_i32_e32 v167, 31, v166
	v_mov_b32_e32 v202, v128
	v_mov_b32_e32 v203, v136
	v_mov_b32_e32 v136, v129
	v_mad_i64_i32 v[128:129], s[0:1], v162, s53, v[160:161]
	v_lshlrev_b64 v[170:171], 1, v[166:167]
	v_lshl_add_u64 v[208:209], v[128:129], 0, v[170:171]
	v_mov_b32_e32 v204, v134
	v_mov_b32_e32 v206, v130
	v_mov_b32_e32 v207, v138
	v_mov_b32_e32 v200, v132
	v_mov_b32_e32 v201, v140
	v_mov_b32_e32 v140, v133
	v_mov_b32_e32 v205, v142
	v_mov_b32_e32 v142, v135
	s_waitcnt vmcnt(0)
	v_pk_mul_f32 v[210:211], v[164:165], s[20:21] op_sel_hi:[1,0]
	s_nop 0
	v_fma_f32 v128, -v210, v210, v211
	v_mov_b32_e32 v169, v66
	v_max_f32_e32 v66, 0, v128
	v_add_f32_e32 v66, 0x3727c5ac, v66
	v_mov_b32_e32 v129, v74
	v_mul_f32_e32 v74, 0x4f800000, v66
	v_cmp_gt_f32_e32 vcc, s54, v66
	v_mov_b32_e32 v167, v78
	v_mov_b32_e32 v173, v76
	v_cndmask_b32_e32 v66, v66, v74, vcc
	v_sqrt_f32_e32 v74, v66
	v_mov_b32_e32 v172, v188
	v_mov_b32_e32 v133, v72
	v_mov_b32_e32 v165, v68
	v_add_u32_e32 v78, -1, v74
	v_add_u32_e32 v130, 1, v74
	v_fma_f32 v134, -v78, v74, v66
	v_fma_f32 v138, -v130, v74, v66
	v_cmp_ge_f32_e64 s[0:1], 0, v134
	v_mov_b32_e32 v132, v192
	v_mov_b32_e32 v164, v144
	v_cndmask_b32_e64 v74, v74, v78, s[0:1]
	v_cmp_lt_f32_e64 s[0:1], 0, v138
	v_mov_b32_e32 v68, v145
	v_pk_fma_f32 v[144:145], v[172:173], v[210:211], v[200:201] op_sel_hi:[1,0,1] neg_lo:[1,0,0] neg_hi:[1,0,0]
	v_cndmask_b32_e64 v74, v74, v130, s[0:1]
	v_mul_f32_e32 v78, 0x37800000, v74
	v_cndmask_b32_e32 v74, v74, v78, vcc
	v_cmp_class_f32_e32 vcc, v66, v186
	v_mov_b32_e32 v76, v189
	v_mov_b32_e32 v72, v193
	v_cndmask_b32_e32 v66, v74, v66, vcc
	v_div_scale_f32 v74, s[0:1], v66, v66, 1.0
	v_rcp_f32_e32 v78, v74
	v_div_scale_f32 v130, vcc, 1.0, v66, 1.0
	v_pk_fma_f32 v[140:141], v[76:77], v[210:211], v[140:141] op_sel_hi:[1,0,1] neg_lo:[1,0,0] neg_hi:[1,0,0]
	v_fma_f32 v134, -v74, v78, 1.0
	v_fmac_f32_e32 v78, v134, v78
	v_mul_f32_e32 v134, v130, v78
	v_fma_f32 v138, -v74, v134, v130
	v_fmac_f32_e32 v134, v138, v78
	v_fma_f32 v74, -v74, v134, v130
	v_div_fmas_f32 v74, v74, v78, v134
	v_div_fixup_f32 v130, v74, v66, 1.0
	v_pk_fma_f32 v[144:145], v[144:145], v[130:131], v[132:133] op_sel_hi:[1,0,1]
	v_pk_fma_f32 v[140:141], v[140:141], v[130:131], v[72:73] op_sel_hi:[1,0,1]
	v_mul_f32_e32 v66, 0xbfb8aa3b, v145
	v_exp_f32_e32 v66, v66
	v_mul_f32_e32 v78, 0xbfb8aa3b, v141
	v_exp_f32_e32 v78, v78
	v_mov_b32_e32 v166, v190
	v_add_f32_e32 v66, 1.0, v66
	v_rcp_f32_e32 v66, v66
	v_mov_b32_e32 v175, v64
	v_mov_b32_e32 v174, v196
	v_mov_b32_e32 v64, v197
	v_mov_b32_e32 v128, v194
	v_pk_fma_f32 v[192:193], v[166:167], v[210:211], v[204:205] op_sel_hi:[1,0,1] neg_lo:[1,0,0] neg_hi:[1,0,0]
	v_pk_fma_f32 v[188:189], v[174:175], v[210:211], v[202:203] op_sel_hi:[1,0,1] neg_lo:[1,0,0] neg_hi:[1,0,0]
	v_pk_fma_f32 v[136:137], v[64:65], v[210:211], v[136:137] op_sel_hi:[1,0,1] neg_lo:[1,0,0] neg_hi:[1,0,0]
	v_pk_fma_f32 v[192:193], v[192:193], v[130:131], v[128:129] op_sel_hi:[1,0,1]
	v_add_f32_e32 v78, 1.0, v78
	v_pk_fma_f32 v[188:189], v[188:189], v[130:131], v[164:165] op_sel_hi:[1,0,1]
	v_pk_fma_f32 v[200:201], v[136:137], v[130:131], v[68:69] op_sel_hi:[1,0,1]
	v_mul_f32_e32 v136, 0xbfb8aa3b, v193
	v_rcp_f32_e32 v78, v78
	v_mul_f32_e32 v66, v145, v66
	v_mul_f32_e32 v74, 0xbfb8aa3b, v189
	v_mul_f32_e32 v144, v144, v66
	v_exp_f32_e32 v66, v136
	v_mul_f32_e32 v134, 0xbfb8aa3b, v201
	v_exp_f32_e32 v74, v74
	v_mov_b32_e32 v168, v198
	v_exp_f32_e32 v134, v134
	v_pk_fma_f32 v[196:197], v[168:169], v[210:211], v[206:207] op_sel_hi:[1,0,1] neg_lo:[1,0,0] neg_hi:[1,0,0]
	v_mul_f32_e32 v78, v141, v78
	v_mov_b32_e32 v136, v146
	v_mov_b32_e32 v137, v70
	v_mul_f32_e32 v163, v140, v78
	v_pk_fma_f32 v[140:141], v[196:197], v[130:131], v[136:137] op_sel_hi:[1,0,1]
	v_add_f32_e32 v66, 1.0, v66
	v_add_f32_e32 v74, 1.0, v74
	v_rcp_f32_e32 v66, v66
	v_mul_f32_e32 v70, 0xbfb8aa3b, v141
	v_add_f32_e32 v134, 1.0, v134
	v_rcp_f32_e32 v74, v74
	v_exp_f32_e32 v70, v70
	v_rcp_f32_e32 v134, v134
	v_mul_f32_e32 v66, v193, v66
	v_mul_f32_e32 v74, v189, v74
	v_mul_f32_e32 v187, v192, v66
	v_add_f32_e32 v66, 1.0, v70
	v_mul_f32_e32 v134, v201, v134
; __device__ __forceinline__ unsigned cvt_pk_bf16(float lo, float hi) { unsigned r; asm volatile("v_cvt_pk_bf16_f32 %0, %1, %2" : "=v"(r) : "v"(lo), "v"(hi)); return r; }
; __device__ __forceinline__ float siluf_(float x) { return x * sigmoidf_(x); }
; __device__ __forceinline__ f32x2 ln_stats(f32x2 sm) { const float mu = sm[0] * (1.f / D); const float var = fmaxf(sm[1] * (1.f / D) - mu * mu, 0.f); return (f32x2){mu, 1.0f / sqrtf(var + LN_EPS)}; }
;     __device__ __forceinline__ void operator()(const f32x4 (&acc)[2][2][4][2], const Unit& u, int wr, int wc, int fr, int fq) const {
;     ...
;         for (int ai = 0; ai < 2; ++ai)
; #pragma unroll
;             for (int m = 0; m < 4; ++m) {
;                 const int r = row0 + ai * HALF + m * 16;
;                 bf16_t* rowp = H + (size_t)r * ldh + col0;
;                 f32x2 st = (f32x2){0.f, 1.f};
;                 if (rsum) st = ln_stats(*(const f32x2*)(rsum + 2 * (size_t)r));
;                 f32x4 v0, v1;
; #pragma unroll
;                 for (int j = 0; j < 4; ++j) {
;                     const float g0 = st[1] * (acc[ai][0][m][0][j] - st[0] * s1[0][0][j]) + s2[0][0][j], u0 = st[1] * (acc[ai][1][m][0][j] - st[0] * s1[1][0][j]) + s2[1][0][j];
;                     const float g1 = st[1] * (acc[ai][0][m][1][j] - st[0] * s1[0][1][j]) + s2[0][1][j], u1 = st[1] * (acc[ai][1][m][1][j] - st[0] * s1[1][1][j]) + s2[1][1][j];
;                     v0[j] = siluf_(g0) * u0; v1[j] = siluf_(g1) * u1;
;                 }
;                 u32x4 w; w.x = cvt_pk_bf16(v0[0], v0[1]); w.y = cvt_pk_bf16(v0[2], v0[3]); w.z = cvt_pk_bf16(v1[0], v1[1]); w.w = cvt_pk_bf16(v1[2], v1[3]);
;                 *(u32x4*)rowp = w;
	v_mul_f32_e32 v145, v188, v74
	v_rcp_f32_e32 v188, v66
	v_mov_b32_e32 v78, v191
	v_mov_b32_e32 v66, v199
	v_mov_b32_e32 v138, v131
	v_mul_f32_e32 v146, v200, v134
	v_pk_fma_f32 v[134:135], v[78:79], v[210:211], v[142:143] op_sel_hi:[1,0,1] neg_lo:[1,0,0] neg_hi:[1,0,0]
	v_mov_b32_e32 v74, v195
	v_pk_fma_f32 v[138:139], v[66:67], v[210:211], v[138:139] op_sel_hi:[1,0,1] neg_lo:[1,0,0] neg_hi:[1,0,0]
	v_mov_b32_e32 v70, v147
	v_pk_fma_f32 v[134:135], v[134:135], v[130:131], v[74:75] op_sel_hi:[1,0,1]
	v_pk_fma_f32 v[130:131], v[138:139], v[130:131], v[70:71] op_sel_hi:[1,0,1]
	v_mul_f32_e32 v138, 0xbfb8aa3b, v135
	v_mul_f32_e32 v139, 0xbfb8aa3b, v131
	v_exp_f32_e32 v139, v139
	v_exp_f32_e32 v138, v138
	v_mul_f32_e32 v141, v141, v188
	v_mul_f32_e32 v141, v140, v141
	v_add_f32_e32 v139, 1.0, v139
	v_add_f32_e32 v138, 1.0, v138
	v_rcp_f32_e32 v139, v139
	v_rcp_f32_e32 v138, v138
	v_mul_f32_e32 v131, v131, v139
	v_mul_f32_e32 v135, v135, v138
	v_mul_f32_e32 v130, v130, v131
	v_mul_f32_e32 v134, v134, v135
	v_cvt_pk_bf16_f32 v138, v144, v163
	v_cvt_pk_bf16_f32 v139, v187, v134
	v_cvt_pk_bf16_f32 v140, v145, v146
	v_cvt_pk_bf16_f32 v141, v141, v130
	v_or_b32_e32 v130, 16, v162
	v_ashrrev_i32_e32 v131, 31, v130
	global_store_dwordx4 v[208:209], v[138:141], off
	v_lshl_add_u64 v[134:135], v[130:131], 3, s[8:9]
	v_mov_b32_e32 v134, v238
	v_mov_b32_e32 v135, v239
	v_mov_b32_e32 v138, v116
	v_mov_b32_e32 v116, v114
	v_mov_b32_e32 v139, v124
	v_mov_b32_e32 v124, v117
	v_mov_b32_e32 v140, v112
	v_mov_b32_e32 v112, v118
	v_mov_b32_e32 v141, v120
	v_mov_b32_e32 v120, v113
	v_mov_b32_e32 v113, v126
	v_mad_i64_i32 v[130:131], s[0:1], v130, s53, v[160:161]
	v_lshl_add_u64 v[130:131], v[130:131], 0, v[170:171]
	s_nop 0
	v_pk_mul_f32 v[134:135], v[134:135], s[20:21] op_sel_hi:[1,0]
	s_nop 0
	v_fma_f32 v114, -v134, v134, v135
	v_max_f32_e32 v114, 0, v114
	v_add_f32_e32 v114, 0x3727c5ac, v114
	v_mul_f32_e32 v117, 0x4f800000, v114
	v_cmp_gt_f32_e32 vcc, s54, v114
	v_pk_fma_f32 v[138:139], v[172:173], v[134:135], v[138:139] op_sel_hi:[1,0,1] neg_lo:[1,0,0] neg_hi:[1,0,0]
	v_pk_fma_f32 v[140:141], v[174:175], v[134:135], v[140:141] op_sel_hi:[1,0,1] neg_lo:[1,0,0] neg_hi:[1,0,0]
	v_cndmask_b32_e32 v114, v114, v117, vcc
	v_sqrt_f32_e32 v117, v114
	v_pk_fma_f32 v[120:121], v[64:65], v[134:135], v[120:121] op_sel_hi:[1,0,1] neg_lo:[1,0,0] neg_hi:[1,0,0]
	v_pk_fma_f32 v[112:113], v[166:167], v[134:135], v[112:113] op_sel_hi:[1,0,1] neg_lo:[1,0,0] neg_hi:[1,0,0]
	v_pk_fma_f32 v[124:125], v[76:77], v[134:135], v[124:125] op_sel_hi:[1,0,1] neg_lo:[1,0,0] neg_hi:[1,0,0]
	v_add_u32_e32 v118, -1, v117
	v_add_u32_e32 v126, 1, v117
	v_fma_f32 v142, -v118, v117, v114
	v_fma_f32 v143, -v126, v117, v114
	v_cmp_ge_f32_e64 s[0:1], 0, v142
	s_nop 1
	v_cndmask_b32_e64 v117, v117, v118, s[0:1]
	v_cmp_lt_f32_e64 s[0:1], 0, v143
	s_nop 1
	v_cndmask_b32_e64 v117, v117, v126, s[0:1]
	v_mul_f32_e32 v118, 0x37800000, v117
	v_cndmask_b32_e32 v117, v117, v118, vcc
	v_cmp_class_f32_e32 vcc, v114, v186
	s_nop 1
	v_cndmask_b32_e32 v114, v117, v114, vcc
	v_div_scale_f32 v117, s[0:1], v114, v114, 1.0
	v_rcp_f32_e32 v118, v117
	v_div_scale_f32 v126, vcc, 1.0, v114, 1.0
	v_fma_f32 v142, -v117, v118, 1.0
	v_fmac_f32_e32 v118, v142, v118
	v_mul_f32_e32 v142, v126, v118
	v_fma_f32 v143, -v117, v142, v126
	v_fmac_f32_e32 v142, v143, v118
	v_fma_f32 v117, -v117, v142, v126
	v_div_fmas_f32 v117, v117, v118, v142
	v_div_fixup_f32 v114, v117, v114, 1.0
	v_pk_fma_f32 v[138:139], v[138:139], v[114:115], v[132:133] op_sel_hi:[1,0,1]
	v_pk_fma_f32 v[140:141], v[140:141], v[114:115], v[164:165] op_sel_hi:[1,0,1]
	v_mul_f32_e32 v117, 0xbfb8aa3b, v139
	v_mul_f32_e32 v118, 0xbfb8aa3b, v141
	v_exp_f32_e32 v117, v117
	v_exp_f32_e32 v118, v118
	v_pk_fma_f32 v[120:121], v[120:121], v[114:115], v[68:69] op_sel_hi:[1,0,1]
	v_pk_fma_f32 v[112:113], v[112:113], v[114:115], v[128:129] op_sel_hi:[1,0,1]
	v_add_f32_e32 v117, 1.0, v117
	v_add_f32_e32 v118, 1.0, v118
	v_rcp_f32_e32 v117, v117
	v_rcp_f32_e32 v118, v118
	v_pk_fma_f32 v[124:125], v[124:125], v[114:115], v[72:73] op_sel_hi:[1,0,1]
	v_mul_f32_e32 v142, 0xbfb8aa3b, v121
	v_mul_f32_e32 v117, v139, v117
	v_mul_f32_e32 v118, v141, v118
	v_mul_f32_e32 v138, v138, v117
	v_mul_f32_e32 v117, 0xbfb8aa3b, v113
	v_mul_f32_e32 v126, 0xbfb8aa3b, v125
	v_exp_f32_e32 v142, v142
	v_mul_f32_e32 v139, v140, v118
	v_exp_f32_e32 v118, v117
	v_exp_f32_e32 v126, v126
	v_mov_b32_e32 v117, v122
	v_pk_fma_f32 v[116:117], v[168:169], v[134:135], v[116:117] op_sel_hi:[1,0,1] neg_lo:[1,0,0] neg_hi:[1,0,0]
	v_add_f32_e32 v142, 1.0, v142
	v_pk_fma_f32 v[116:117], v[116:117], v[114:115], v[136:137] op_sel_hi:[1,0,1]
	v_add_f32_e32 v118, 1.0, v118
	v_add_f32_e32 v126, 1.0, v126
	v_rcp_f32_e32 v142, v142
	v_rcp_f32_e32 v118, v118
	v_mul_f32_e32 v122, 0xbfb8aa3b, v117
	v_rcp_f32_e32 v126, v126
	v_exp_f32_e32 v122, v122
	v_mul_f32_e32 v121, v121, v142
	v_mul_f32_e32 v113, v113, v118
	v_mul_f32_e32 v125, v125, v126
	v_mul_f32_e32 v120, v120, v121
	v_mul_f32_e32 v121, v112, v113
	v_add_f32_e32 v112, 1.0, v122
	v_mov_b32_e32 v126, v119
	v_mul_f32_e32 v124, v124, v125
	v_rcp_f32_e32 v125, v112
	v_pk_fma_f32 v[112:113], v[78:79], v[134:135], v[126:127] op_sel_hi:[1,0,1] neg_lo:[1,0,0] neg_hi:[1,0,0]
	v_mov_b32_e32 v122, v115
	v_pk_fma_f32 v[112:113], v[112:113], v[114:115], v[74:75] op_sel_hi:[1,0,1]
	v_pk_fma_f32 v[118:119], v[66:67], v[134:135], v[122:123] op_sel_hi:[1,0,1] neg_lo:[1,0,0] neg_hi:[1,0,0]
	v_mul_f32_e32 v117, v117, v125
	v_pk_fma_f32 v[114:115], v[118:119], v[114:115], v[70:71] op_sel_hi:[1,0,1]
	v_mul_f32_e32 v118, 0xbfb8aa3b, v113
	v_exp_f32_e32 v118, v118
	v_mul_f32_e32 v119, 0xbfb8aa3b, v115
; __device__ __forceinline__ unsigned cvt_pk_bf16(float lo, float hi) { unsigned r; asm volatile("v_cvt_pk_bf16_f32 %0, %1, %2" : "=v"(r) : "v"(lo), "v"(hi)); return r; }
; __device__ __forceinline__ float siluf_(float x) { return x * sigmoidf_(x); }
; __device__ __forceinline__ f32x2 ln_stats(f32x2 sm) { const float mu = sm[0] * (1.f / D); const float var = fmaxf(sm[1] * (1.f / D) - mu * mu, 0.f); return (f32x2){mu, 1.0f / sqrtf(var + LN_EPS)}; }
;     __device__ __forceinline__ void operator()(const f32x4 (&acc)[2][2][4][2], const Unit& u, int wr, int wc, int fr, int fq) const {
;     ...
;         for (int ai = 0; ai < 2; ++ai)
; #pragma unroll
;             for (int m = 0; m < 4; ++m) {
;                 const int r = row0 + ai * HALF + m * 16;
;                 bf16_t* rowp = H + (size_t)r * ldh + col0;
;                 f32x2 st = (f32x2){0.f, 1.f};
;                 if (rsum) st = ln_stats(*(const f32x2*)(rsum + 2 * (size_t)r));
;                 f32x4 v0, v1;
; #pragma unroll
;                 for (int j = 0; j < 4; ++j) {
;                     const float g0 = st[1] * (acc[ai][0][m][0][j] - st[0] * s1[0][0][j]) + s2[0][0][j], u0 = st[1] * (acc[ai][1][m][0][j] - st[0] * s1[1][0][j]) + s2[1][0][j];
;                     const float g1 = st[1] * (acc[ai][0][m][1][j] - st[0] * s1[0][1][j]) + s2[0][1][j], u1 = st[1] * (acc[ai][1][m][1][j] - st[0] * s1[1][1][j]) + s2[1][1][j];
;                     v0[j] = siluf_(g0) * u0; v1[j] = siluf_(g1) * u1;
;                 }
;                 u32x4 w; w.x = cvt_pk_bf16(v0[0], v0[1]); w.y = cvt_pk_bf16(v0[2], v0[3]); w.z = cvt_pk_bf16(v1[0], v1[1]); w.w = cvt_pk_bf16(v1[2], v1[3]);
;                 *(u32x4*)rowp = w;
	v_exp_f32_e32 v119, v119
	v_mul_f32_e32 v116, v116, v117
	v_add_f32_e32 v118, 1.0, v118
	v_rcp_f32_e32 v118, v118
	v_add_f32_e32 v119, 1.0, v119
	v_rcp_f32_e32 v119, v119
	v_mov_b32_e32 v117, v108
	v_mul_f32_e32 v113, v113, v118
	v_mul_f32_e32 v113, v112, v113
	v_mul_f32_e32 v112, v115, v119
	v_mul_f32_e32 v115, v114, v112
	v_cvt_pk_bf16_f32 v112, v138, v124
	v_cvt_pk_bf16_f32 v113, v121, v113
	v_cvt_pk_bf16_f32 v114, v139, v120
	v_cvt_pk_bf16_f32 v115, v116, v115
	global_store_dwordx4 v[130:131], v[112:115], off
	v_mov_b32_e32 v116, v100
	v_mov_b32_e32 v100, v98
	v_or_b32_e32 v112, 32, v162
	v_ashrrev_i32_e32 v113, 31, v112
	v_lshl_add_u64 v[114:115], v[112:113], 3, s[8:9]
	v_mov_b32_e32 v114, v240
	v_mov_b32_e32 v115, v241
	v_mov_b32_e32 v118, v96
	v_mov_b32_e32 v96, v102
	v_mov_b32_e32 v108, v101
	v_mov_b32_e32 v101, v106
	v_mov_b32_e32 v119, v104
	v_mov_b32_e32 v104, v97
	v_mov_b32_e32 v97, v110
	v_mad_i64_i32 v[112:113], s[0:1], v112, s53, v[160:161]
	v_lshl_add_u64 v[112:113], v[112:113], 0, v[170:171]
	s_nop 0
	v_pk_mul_f32 v[114:115], v[114:115], s[20:21] op_sel_hi:[1,0]
	s_nop 0
	v_fma_f32 v98, -v114, v114, v115
	v_max_f32_e32 v98, 0, v98
	v_add_f32_e32 v98, 0x3727c5ac, v98
	v_mul_f32_e32 v102, 0x4f800000, v98
	v_cmp_gt_f32_e32 vcc, s54, v98
	v_pk_fma_f32 v[116:117], v[172:173], v[114:115], v[116:117] op_sel_hi:[1,0,1] neg_lo:[1,0,0] neg_hi:[1,0,0]
	v_pk_fma_f32 v[118:119], v[174:175], v[114:115], v[118:119] op_sel_hi:[1,0,1] neg_lo:[1,0,0] neg_hi:[1,0,0]
	v_cndmask_b32_e32 v98, v98, v102, vcc
	v_sqrt_f32_e32 v102, v98
	v_pk_fma_f32 v[104:105], v[64:65], v[114:115], v[104:105] op_sel_hi:[1,0,1] neg_lo:[1,0,0] neg_hi:[1,0,0]
	v_pk_fma_f32 v[96:97], v[166:167], v[114:115], v[96:97] op_sel_hi:[1,0,1] neg_lo:[1,0,0] neg_hi:[1,0,0]
	v_pk_fma_f32 v[108:109], v[76:77], v[114:115], v[108:109] op_sel_hi:[1,0,1] neg_lo:[1,0,0] neg_hi:[1,0,0]
	v_add_u32_e32 v106, -1, v102
	v_add_u32_e32 v110, 1, v102
	v_fma_f32 v120, -v106, v102, v98
	v_fma_f32 v121, -v110, v102, v98
	v_cmp_ge_f32_e64 s[0:1], 0, v120
	v_pk_fma_f32 v[100:101], v[168:169], v[114:115], v[100:101] op_sel_hi:[1,0,1] neg_lo:[1,0,0] neg_hi:[1,0,0]
	s_nop 0
	v_cndmask_b32_e64 v102, v102, v106, s[0:1]
	v_cmp_lt_f32_e64 s[0:1], 0, v121
	s_nop 1
	v_cndmask_b32_e64 v102, v102, v110, s[0:1]
	v_mul_f32_e32 v106, 0x37800000, v102
	v_cndmask_b32_e32 v102, v102, v106, vcc
	v_cmp_class_f32_e32 vcc, v98, v186
	s_nop 1
	v_cndmask_b32_e32 v98, v102, v98, vcc
	v_div_scale_f32 v102, s[0:1], v98, v98, 1.0
	v_rcp_f32_e32 v106, v102
	v_div_scale_f32 v110, vcc, 1.0, v98, 1.0
	v_fma_f32 v120, -v102, v106, 1.0
	v_fmac_f32_e32 v106, v120, v106
	v_mul_f32_e32 v120, v110, v106
	v_fma_f32 v121, -v102, v120, v110
	v_fmac_f32_e32 v120, v121, v106
	v_fma_f32 v102, -v102, v120, v110
	v_div_fmas_f32 v102, v102, v106, v120
	v_div_fixup_f32 v98, v102, v98, 1.0
	v_pk_fma_f32 v[116:117], v[116:117], v[98:99], v[132:133] op_sel_hi:[1,0,1]
	v_pk_fma_f32 v[118:119], v[118:119], v[98:99], v[164:165] op_sel_hi:[1,0,1]
	v_mul_f32_e32 v102, 0xbfb8aa3b, v117
	v_mul_f32_e32 v106, 0xbfb8aa3b, v119
	v_exp_f32_e32 v102, v102
	v_exp_f32_e32 v106, v106
	v_pk_fma_f32 v[104:105], v[104:105], v[98:99], v[68:69] op_sel_hi:[1,0,1]
	v_pk_fma_f32 v[96:97], v[96:97], v[98:99], v[128:129] op_sel_hi:[1,0,1]
	v_add_f32_e32 v102, 1.0, v102
	v_pk_fma_f32 v[108:109], v[108:109], v[98:99], v[72:73] op_sel_hi:[1,0,1]
	v_mul_f32_e32 v120, 0xbfb8aa3b, v105
	v_mul_f32_e32 v121, 0xbfb8aa3b, v97
	v_add_f32_e32 v106, 1.0, v106
	v_rcp_f32_e32 v102, v102
	v_mul_f32_e32 v110, 0xbfb8aa3b, v109
	v_exp_f32_e32 v120, v120
	v_exp_f32_e32 v121, v121
	v_rcp_f32_e32 v106, v106
	v_exp_f32_e32 v110, v110
	v_mul_f32_e32 v102, v117, v102
	v_add_f32_e32 v120, 1.0, v120
	v_mul_f32_e32 v106, v119, v106
	v_mul_f32_e32 v116, v116, v102
	v_pk_fma_f32 v[100:101], v[100:101], v[98:99], v[136:137] op_sel_hi:[1,0,1]
	v_add_f32_e32 v102, 1.0, v121
	v_add_f32_e32 v110, 1.0, v110
	v_rcp_f32_e32 v120, v120
	v_mul_f32_e32 v117, v118, v106
	v_rcp_f32_e32 v102, v102
	v_mul_f32_e32 v106, 0xbfb8aa3b, v101
	v_rcp_f32_e32 v110, v110
	v_exp_f32_e32 v106, v106
	v_mul_f32_e32 v105, v105, v120
	v_mul_f32_e32 v97, v97, v102
	v_mul_f32_e32 v109, v109, v110
	v_mul_f32_e32 v104, v104, v105
	v_mul_f32_e32 v105, v96, v97
	v_add_f32_e32 v96, 1.0, v106
	v_mov_b32_e32 v110, v103
	v_mul_f32_e32 v108, v108, v109
	v_rcp_f32_e32 v109, v96
	v_pk_fma_f32 v[96:97], v[78:79], v[114:115], v[110:111] op_sel_hi:[1,0,1] neg_lo:[1,0,0] neg_hi:[1,0,0]
	v_mov_b32_e32 v106, v99
	v_pk_fma_f32 v[96:97], v[96:97], v[98:99], v[74:75] op_sel_hi:[1,0,1]
	v_pk_fma_f32 v[102:103], v[66:67], v[114:115], v[106:107] op_sel_hi:[1,0,1] neg_lo:[1,0,0] neg_hi:[1,0,0]
	v_mul_f32_e32 v101, v101, v109
	v_pk_fma_f32 v[98:99], v[102:103], v[98:99], v[70:71] op_sel_hi:[1,0,1]
	v_mul_f32_e32 v102, 0xbfb8aa3b, v97
	v_exp_f32_e32 v102, v102
	v_mul_f32_e32 v103, 0xbfb8aa3b, v99
	v_exp_f32_e32 v103, v103
	v_mul_f32_e32 v100, v100, v101
	v_add_f32_e32 v102, 1.0, v102
	v_rcp_f32_e32 v102, v102
	v_add_f32_e32 v103, 1.0, v103
	v_rcp_f32_e32 v103, v103
	v_mov_b32_e32 v101, v92
	v_mul_f32_e32 v97, v97, v102
	v_mul_f32_e32 v97, v96, v97
	v_mul_f32_e32 v96, v99, v103
	v_mul_f32_e32 v99, v98, v96
	v_cvt_pk_bf16_f32 v96, v116, v108
	v_cvt_pk_bf16_f32 v97, v105, v97
	v_cvt_pk_bf16_f32 v98, v117, v104
	v_cvt_pk_bf16_f32 v99, v100, v99
	global_store_dwordx4 v[112:113], v[96:99], off
	v_mov_b32_e32 v100, v84
	v_mov_b32_e32 v84, v82
	v_or_b32_e32 v96, 48, v162
	v_ashrrev_i32_e32 v97, 31, v96
	v_lshl_add_u64 v[98:99], v[96:97], 3, s[8:9]
	v_mov_b32_e32 v98, v242
	v_mov_b32_e32 v99, v243
	v_mov_b32_e32 v102, v80
	v_mov_b32_e32 v80, v86
	v_mov_b32_e32 v92, v85
; __device__ __forceinline__ unsigned cvt_pk_bf16(float lo, float hi) { unsigned r; asm volatile("v_cvt_pk_bf16_f32 %0, %1, %2" : "=v"(r) : "v"(lo), "v"(hi)); return r; }
; __device__ __forceinline__ float siluf_(float x) { return x * sigmoidf_(x); }
; __device__ __forceinline__ f32x2 ln_stats(f32x2 sm) { const float mu = sm[0] * (1.f / D); const float var = fmaxf(sm[1] * (1.f / D) - mu * mu, 0.f); return (f32x2){mu, 1.0f / sqrtf(var + LN_EPS)}; }
;     __device__ __forceinline__ void operator()(const f32x4 (&acc)[2][2][4][2], const Unit& u, int wr, int wc, int fr, int fq) const {
;     ...
;         for (int ai = 0; ai < 2; ++ai)
; #pragma unroll
;             for (int m = 0; m < 4; ++m) {
;                 const int r = row0 + ai * HALF + m * 16;
;                 bf16_t* rowp = H + (size_t)r * ldh + col0;
;                 f32x2 st = (f32x2){0.f, 1.f};
;                 if (rsum) st = ln_stats(*(const f32x2*)(rsum + 2 * (size_t)r));
;                 f32x4 v0, v1;
; #pragma unroll
;                 for (int j = 0; j < 4; ++j) {
;                     const float g0 = st[1] * (acc[ai][0][m][0][j] - st[0] * s1[0][0][j]) + s2[0][0][j], u0 = st[1] * (acc[ai][1][m][0][j] - st[0] * s1[1][0][j]) + s2[1][0][j];
;                     const float g1 = st[1] * (acc[ai][0][m][1][j] - st[0] * s1[0][1][j]) + s2[0][1][j], u1 = st[1] * (acc[ai][1][m][1][j] - st[0] * s1[1][1][j]) + s2[1][1][j];
;                     v0[j] = siluf_(g0) * u0; v1[j] = siluf_(g1) * u1;
;                 }
;                 u32x4 w; w.x = cvt_pk_bf16(v0[0], v0[1]); w.y = cvt_pk_bf16(v0[2], v0[3]); w.z = cvt_pk_bf16(v1[0], v1[1]); w.w = cvt_pk_bf16(v1[2], v1[3]);
;                 *(u32x4*)rowp = w;
	v_mov_b32_e32 v85, v90
	v_mov_b32_e32 v103, v88
	v_mov_b32_e32 v88, v81
	v_mov_b32_e32 v81, v94
	v_mad_i64_i32 v[96:97], s[0:1], v96, s53, v[160:161]
	v_lshl_add_u64 v[96:97], v[96:97], 0, v[170:171]
	s_nop 0
	v_pk_mul_f32 v[98:99], v[98:99], s[20:21] op_sel_hi:[1,0]
	s_nop 0
	v_fma_f32 v82, -v98, v98, v99
	v_max_f32_e32 v82, 0, v82
	v_add_f32_e32 v82, 0x3727c5ac, v82
	v_mul_f32_e32 v86, 0x4f800000, v82
	v_cmp_gt_f32_e32 vcc, s54, v82
	v_pk_fma_f32 v[100:101], v[172:173], v[98:99], v[100:101] op_sel_hi:[1,0,1] neg_lo:[1,0,0] neg_hi:[1,0,0]
	v_pk_fma_f32 v[102:103], v[174:175], v[98:99], v[102:103] op_sel_hi:[1,0,1] neg_lo:[1,0,0] neg_hi:[1,0,0]
	v_cndmask_b32_e32 v82, v82, v86, vcc
	v_sqrt_f32_e32 v86, v82
	v_pk_fma_f32 v[88:89], v[64:65], v[98:99], v[88:89] op_sel_hi:[1,0,1] neg_lo:[1,0,0] neg_hi:[1,0,0]
	v_pk_fma_f32 v[80:81], v[166:167], v[98:99], v[80:81] op_sel_hi:[1,0,1] neg_lo:[1,0,0] neg_hi:[1,0,0]
	v_pk_fma_f32 v[92:93], v[76:77], v[98:99], v[92:93] op_sel_hi:[1,0,1] neg_lo:[1,0,0] neg_hi:[1,0,0]
	v_add_u32_e32 v90, -1, v86
	v_add_u32_e32 v94, 1, v86
	v_fma_f32 v104, -v90, v86, v82
	v_fma_f32 v105, -v94, v86, v82
	v_cmp_ge_f32_e64 s[0:1], 0, v104
	v_pk_fma_f32 v[84:85], v[168:169], v[98:99], v[84:85] op_sel_hi:[1,0,1] neg_lo:[1,0,0] neg_hi:[1,0,0]
	s_nop 0
	v_cndmask_b32_e64 v86, v86, v90, s[0:1]
	v_cmp_lt_f32_e64 s[0:1], 0, v105
	s_nop 1
	v_cndmask_b32_e64 v86, v86, v94, s[0:1]
	v_mul_f32_e32 v90, 0x37800000, v86
	v_cndmask_b32_e32 v86, v86, v90, vcc
	v_cmp_class_f32_e32 vcc, v82, v186
	s_nop 1
	v_cndmask_b32_e32 v82, v86, v82, vcc
	v_div_scale_f32 v86, s[0:1], v82, v82, 1.0
	v_rcp_f32_e32 v90, v86
	v_div_scale_f32 v94, vcc, 1.0, v82, 1.0
	v_fma_f32 v104, -v86, v90, 1.0
	v_fmac_f32_e32 v90, v104, v90
	v_mul_f32_e32 v104, v94, v90
	v_fma_f32 v105, -v86, v104, v94
	v_fmac_f32_e32 v104, v105, v90
	v_fma_f32 v86, -v86, v104, v94
	v_div_fmas_f32 v86, v86, v90, v104
	v_div_fixup_f32 v82, v86, v82, 1.0
	v_pk_fma_f32 v[100:101], v[100:101], v[82:83], v[132:133] op_sel_hi:[1,0,1]
	v_pk_fma_f32 v[102:103], v[102:103], v[82:83], v[164:165] op_sel_hi:[1,0,1]
	v_mul_f32_e32 v86, 0xbfb8aa3b, v101
	v_mul_f32_e32 v90, 0xbfb8aa3b, v103
	v_exp_f32_e32 v86, v86
	v_exp_f32_e32 v90, v90
	v_pk_fma_f32 v[88:89], v[88:89], v[82:83], v[68:69] op_sel_hi:[1,0,1]
	v_pk_fma_f32 v[80:81], v[80:81], v[82:83], v[128:129] op_sel_hi:[1,0,1]
	v_pk_fma_f32 v[92:93], v[92:93], v[82:83], v[72:73] op_sel_hi:[1,0,1]
	v_mul_f32_e32 v104, 0xbfb8aa3b, v89
	v_mul_f32_e32 v105, 0xbfb8aa3b, v81
	v_add_f32_e32 v86, 1.0, v86
	v_add_f32_e32 v90, 1.0, v90
	v_mul_f32_e32 v94, 0xbfb8aa3b, v93
	v_exp_f32_e32 v104, v104
	v_exp_f32_e32 v105, v105
	v_rcp_f32_e32 v86, v86
	v_rcp_f32_e32 v90, v90
	v_exp_f32_e32 v94, v94
	v_pk_fma_f32 v[84:85], v[84:85], v[82:83], v[136:137] op_sel_hi:[1,0,1]
	v_add_f32_e32 v104, 1.0, v104
	v_add_f32_e32 v105, 1.0, v105
	v_mul_f32_e32 v86, v101, v86
	v_mul_f32_e32 v90, v103, v90
	v_add_f32_e32 v94, 1.0, v94
	v_rcp_f32_e32 v104, v104
	v_mul_f32_e32 v100, v100, v86
	v_mul_f32_e32 v101, v102, v90
	v_rcp_f32_e32 v86, v105
	v_mul_f32_e32 v90, 0xbfb8aa3b, v85
	v_rcp_f32_e32 v94, v94
	v_exp_f32_e32 v90, v90
	v_mul_f32_e32 v89, v89, v104
	v_mul_f32_e32 v81, v81, v86
	v_mul_f32_e32 v93, v93, v94
	v_mul_f32_e32 v88, v88, v89
	v_mul_f32_e32 v89, v80, v81
	v_add_f32_e32 v80, 1.0, v90
	v_mov_b32_e32 v94, v87
	v_mul_f32_e32 v92, v92, v93
	v_rcp_f32_e32 v93, v80
	v_pk_fma_f32 v[80:81], v[78:79], v[98:99], v[94:95] op_sel_hi:[1,0,1] neg_lo:[1,0,0] neg_hi:[1,0,0]
	v_mov_b32_e32 v90, v83
	v_pk_fma_f32 v[80:81], v[80:81], v[82:83], v[74:75] op_sel_hi:[1,0,1]
	v_pk_fma_f32 v[86:87], v[66:67], v[98:99], v[90:91] op_sel_hi:[1,0,1] neg_lo:[1,0,0] neg_hi:[1,0,0]
	v_mul_f32_e32 v85, v85, v93
	v_pk_fma_f32 v[82:83], v[86:87], v[82:83], v[70:71] op_sel_hi:[1,0,1]
	v_mul_f32_e32 v86, 0xbfb8aa3b, v81
	v_exp_f32_e32 v86, v86
	v_mul_f32_e32 v87, 0xbfb8aa3b, v83
	v_exp_f32_e32 v87, v87
	v_mul_f32_e32 v84, v84, v85
	v_add_f32_e32 v86, 1.0, v86
	v_rcp_f32_e32 v86, v86
	v_add_f32_e32 v87, 1.0, v87
	v_rcp_f32_e32 v87, v87
	v_mov_b32_e32 v85, v60
	v_mul_f32_e32 v81, v81, v86
	v_mul_f32_e32 v81, v80, v81
	v_mul_f32_e32 v80, v83, v87
	v_mul_f32_e32 v83, v82, v80
	v_cvt_pk_bf16_f32 v80, v100, v92
	v_cvt_pk_bf16_f32 v81, v89, v81
	v_cvt_pk_bf16_f32 v82, v101, v88
	v_cvt_pk_bf16_f32 v83, v84, v83
	global_store_dwordx4 v[96:97], v[80:83], off
	v_mov_b32_e32 v84, v52
	v_mov_b32_e32 v52, v50
	v_add_u32_e32 v80, 0x80, v162
	v_ashrrev_i32_e32 v81, 31, v80
	v_lshl_add_u64 v[82:83], v[80:81], 3, s[8:9]
	v_mov_b32_e32 v82, v244
	v_mov_b32_e32 v83, v245
	v_mov_b32_e32 v86, v48
	v_mov_b32_e32 v48, v54
	v_mov_b32_e32 v60, v53
	v_mov_b32_e32 v53, v58
	v_mov_b32_e32 v87, v56
	v_mov_b32_e32 v56, v49
	v_mov_b32_e32 v49, v62
	v_mad_i64_i32 v[80:81], s[0:1], v80, s53, v[160:161]
	v_lshl_add_u64 v[80:81], v[80:81], 0, v[170:171]
	s_nop 0
	v_pk_mul_f32 v[82:83], v[82:83], s[20:21] op_sel_hi:[1,0]
	s_nop 0
	v_fma_f32 v50, -v82, v82, v83
	v_max_f32_e32 v50, 0, v50
	v_add_f32_e32 v50, 0x3727c5ac, v50
	v_mul_f32_e32 v54, 0x4f800000, v50
	v_cmp_gt_f32_e32 vcc, s54, v50
	v_pk_fma_f32 v[56:57], v[64:65], v[82:83], v[56:57] op_sel_hi:[1,0,1] neg_lo:[1,0,0] neg_hi:[1,0,0]
	v_pk_fma_f32 v[48:49], v[166:167], v[82:83], v[48:49] op_sel_hi:[1,0,1] neg_lo:[1,0,0] neg_hi:[1,0,0]
	v_cndmask_b32_e32 v50, v50, v54, vcc
	v_sqrt_f32_e32 v54, v50
	v_pk_fma_f32 v[86:87], v[174:175], v[82:83], v[86:87] op_sel_hi:[1,0,1] neg_lo:[1,0,0] neg_hi:[1,0,0]
	v_pk_fma_f32 v[60:61], v[76:77], v[82:83], v[60:61] op_sel_hi:[1,0,1] neg_lo:[1,0,0] neg_hi:[1,0,0]
	v_pk_fma_f32 v[84:85], v[172:173], v[82:83], v[84:85] op_sel_hi:[1,0,1] neg_lo:[1,0,0] neg_hi:[1,0,0]
; __device__ __forceinline__ unsigned cvt_pk_bf16(float lo, float hi) { unsigned r; asm volatile("v_cvt_pk_bf16_f32 %0, %1, %2" : "=v"(r) : "v"(lo), "v"(hi)); return r; }
; __device__ __forceinline__ float siluf_(float x) { return x * sigmoidf_(x); }
; __device__ __forceinline__ f32x2 ln_stats(f32x2 sm) { const float mu = sm[0] * (1.f / D); const float var = fmaxf(sm[1] * (1.f / D) - mu * mu, 0.f); return (f32x2){mu, 1.0f / sqrtf(var + LN_EPS)}; }
;     __device__ __forceinline__ void operator()(const f32x4 (&acc)[2][2][4][2], const Unit& u, int wr, int wc, int fr, int fq) const {
;     ...
;         for (int ai = 0; ai < 2; ++ai)
; #pragma unroll
;             for (int m = 0; m < 4; ++m) {
;                 const int r = row0 + ai * HALF + m * 16;
;                 bf16_t* rowp = H + (size_t)r * ldh + col0;
;                 f32x2 st = (f32x2){0.f, 1.f};
;                 if (rsum) st = ln_stats(*(const f32x2*)(rsum + 2 * (size_t)r));
;                 f32x4 v0, v1;
; #pragma unroll
;                 for (int j = 0; j < 4; ++j) {
;                     const float g0 = st[1] * (acc[ai][0][m][0][j] - st[0] * s1[0][0][j]) + s2[0][0][j], u0 = st[1] * (acc[ai][1][m][0][j] - st[0] * s1[1][0][j]) + s2[1][0][j];
;                     const float g1 = st[1] * (acc[ai][0][m][1][j] - st[0] * s1[0][1][j]) + s2[0][1][j], u1 = st[1] * (acc[ai][1][m][1][j] - st[0] * s1[1][1][j]) + s2[1][1][j];
;                     v0[j] = siluf_(g0) * u0; v1[j] = siluf_(g1) * u1;
;                 }
;                 u32x4 w; w.x = cvt_pk_bf16(v0[0], v0[1]); w.y = cvt_pk_bf16(v0[2], v0[3]); w.z = cvt_pk_bf16(v1[0], v1[1]); w.w = cvt_pk_bf16(v1[2], v1[3]);
;                 *(u32x4*)rowp = w;
	v_add_u32_e32 v58, -1, v54
	v_add_u32_e32 v62, 1, v54
	v_fma_f32 v88, -v58, v54, v50
	v_fma_f32 v89, -v62, v54, v50
	v_cmp_ge_f32_e64 s[0:1], 0, v88
	v_pk_fma_f32 v[52:53], v[168:169], v[82:83], v[52:53] op_sel_hi:[1,0,1] neg_lo:[1,0,0] neg_hi:[1,0,0]
	s_nop 0
	v_cndmask_b32_e64 v54, v54, v58, s[0:1]
	v_cmp_lt_f32_e64 s[0:1], 0, v89
	s_nop 1
	v_cndmask_b32_e64 v54, v54, v62, s[0:1]
	v_mul_f32_e32 v58, 0x37800000, v54
	v_cndmask_b32_e32 v54, v54, v58, vcc
	v_cmp_class_f32_e32 vcc, v50, v186
	s_nop 1
	v_cndmask_b32_e32 v50, v54, v50, vcc
	v_div_scale_f32 v54, s[0:1], v50, v50, 1.0
	v_rcp_f32_e32 v58, v54
	v_div_scale_f32 v62, vcc, 1.0, v50, 1.0
	v_fma_f32 v88, -v54, v58, 1.0
	v_fmac_f32_e32 v58, v88, v58
	v_mul_f32_e32 v88, v62, v58
	v_fma_f32 v89, -v54, v88, v62
	v_fmac_f32_e32 v88, v89, v58
	v_fma_f32 v54, -v54, v88, v62
	v_div_fmas_f32 v54, v54, v58, v88
	v_div_fixup_f32 v50, v54, v50, 1.0
	v_pk_fma_f32 v[56:57], v[56:57], v[50:51], v[68:69] op_sel_hi:[1,0,1]
	v_pk_fma_f32 v[48:49], v[48:49], v[50:51], v[128:129] op_sel_hi:[1,0,1]
	v_pk_fma_f32 v[86:87], v[86:87], v[50:51], v[164:165] op_sel_hi:[1,0,1]
	v_pk_fma_f32 v[60:61], v[60:61], v[50:51], v[72:73] op_sel_hi:[1,0,1]
	v_mul_f32_e32 v88, 0xbfb8aa3b, v57
	v_mul_f32_e32 v89, 0xbfb8aa3b, v49
	v_pk_fma_f32 v[84:85], v[84:85], v[50:51], v[132:133] op_sel_hi:[1,0,1]
	v_mul_f32_e32 v58, 0xbfb8aa3b, v87
	v_mul_f32_e32 v62, 0xbfb8aa3b, v61
	v_exp_f32_e32 v88, v88
	v_exp_f32_e32 v89, v89
	v_mul_f32_e32 v54, 0xbfb8aa3b, v85
	v_exp_f32_e32 v58, v58
	v_exp_f32_e32 v62, v62
	v_exp_f32_e32 v54, v54
	v_pk_fma_f32 v[52:53], v[52:53], v[50:51], v[136:137] op_sel_hi:[1,0,1]
	v_add_f32_e32 v88, 1.0, v88
	v_add_f32_e32 v89, 1.0, v89
	v_mul_f32_e32 v90, 0xbfb8aa3b, v53
	v_add_f32_e32 v58, 1.0, v58
	v_add_f32_e32 v62, 1.0, v62
	v_rcp_f32_e32 v88, v88
	v_rcp_f32_e32 v89, v89
	v_exp_f32_e32 v90, v90
	v_add_f32_e32 v54, 1.0, v54
	v_rcp_f32_e32 v58, v58
	v_rcp_f32_e32 v62, v62
	v_rcp_f32_e32 v54, v54
	v_mul_f32_e32 v57, v57, v88
	v_mul_f32_e32 v49, v49, v89
	v_mul_f32_e32 v58, v87, v58
	v_mul_f32_e32 v61, v61, v62
	v_mul_f32_e32 v56, v56, v57
	v_mul_f32_e32 v57, v48, v49
	v_add_f32_e32 v48, 1.0, v90
	v_mov_b32_e32 v62, v55
	v_mul_f32_e32 v54, v85, v54
	v_mul_f32_e32 v85, v86, v58
	v_mul_f32_e32 v60, v60, v61
	v_rcp_f32_e32 v61, v48
	v_pk_fma_f32 v[48:49], v[78:79], v[82:83], v[62:63] op_sel_hi:[1,0,1] neg_lo:[1,0,0] neg_hi:[1,0,0]
	v_mov_b32_e32 v58, v51
	v_mul_f32_e32 v84, v84, v54
	v_pk_fma_f32 v[48:49], v[48:49], v[50:51], v[74:75] op_sel_hi:[1,0,1]
	v_pk_fma_f32 v[54:55], v[66:67], v[82:83], v[58:59] op_sel_hi:[1,0,1] neg_lo:[1,0,0] neg_hi:[1,0,0]
	v_mul_f32_e32 v53, v53, v61
	v_pk_fma_f32 v[50:51], v[54:55], v[50:51], v[70:71] op_sel_hi:[1,0,1]
	v_mul_f32_e32 v54, 0xbfb8aa3b, v49
	v_exp_f32_e32 v54, v54
	v_mul_f32_e32 v55, 0xbfb8aa3b, v51
	v_exp_f32_e32 v55, v55
	v_mul_f32_e32 v52, v52, v53
	v_add_f32_e32 v54, 1.0, v54
	v_rcp_f32_e32 v54, v54
	v_add_f32_e32 v55, 1.0, v55
	v_rcp_f32_e32 v55, v55
	v_mov_b32_e32 v53, v44
	v_mul_f32_e32 v49, v49, v54
	v_mul_f32_e32 v49, v48, v49
	v_mul_f32_e32 v48, v51, v55
	v_mul_f32_e32 v51, v50, v48
	v_cvt_pk_bf16_f32 v48, v84, v60
	v_cvt_pk_bf16_f32 v49, v57, v49
	v_cvt_pk_bf16_f32 v50, v85, v56
	v_cvt_pk_bf16_f32 v51, v52, v51
	global_store_dwordx4 v[80:81], v[48:51], off
	v_mov_b32_e32 v52, v36
	v_mov_b32_e32 v36, v34
	v_add_u32_e32 v48, 0x90, v162
	v_ashrrev_i32_e32 v49, 31, v48
	v_lshl_add_u64 v[50:51], v[48:49], 3, s[8:9]
	v_mov_b32_e32 v50, v246
	v_mov_b32_e32 v51, v247
	v_mov_b32_e32 v54, v32
	v_mov_b32_e32 v32, v38
	v_mov_b32_e32 v44, v37
	v_mov_b32_e32 v37, v42
	v_mov_b32_e32 v55, v40
	v_mov_b32_e32 v40, v33
	v_mov_b32_e32 v33, v46
	v_mad_i64_i32 v[48:49], s[0:1], v48, s53, v[160:161]
	v_lshl_add_u64 v[48:49], v[48:49], 0, v[170:171]
	s_nop 0
	v_pk_mul_f32 v[50:51], v[50:51], s[20:21] op_sel_hi:[1,0]
	s_nop 0
	v_fma_f32 v34, -v50, v50, v51
	v_max_f32_e32 v34, 0, v34
	v_add_f32_e32 v34, 0x3727c5ac, v34
	v_mul_f32_e32 v38, 0x4f800000, v34
	v_cmp_gt_f32_e32 vcc, s54, v34
	v_pk_fma_f32 v[40:41], v[64:65], v[50:51], v[40:41] op_sel_hi:[1,0,1] neg_lo:[1,0,0] neg_hi:[1,0,0]
	v_pk_fma_f32 v[32:33], v[166:167], v[50:51], v[32:33] op_sel_hi:[1,0,1] neg_lo:[1,0,0] neg_hi:[1,0,0]
	v_cndmask_b32_e32 v34, v34, v38, vcc
	v_sqrt_f32_e32 v38, v34
	v_pk_fma_f32 v[54:55], v[174:175], v[50:51], v[54:55] op_sel_hi:[1,0,1] neg_lo:[1,0,0] neg_hi:[1,0,0]
	v_pk_fma_f32 v[44:45], v[76:77], v[50:51], v[44:45] op_sel_hi:[1,0,1] neg_lo:[1,0,0] neg_hi:[1,0,0]
	v_pk_fma_f32 v[52:53], v[172:173], v[50:51], v[52:53] op_sel_hi:[1,0,1] neg_lo:[1,0,0] neg_hi:[1,0,0]
	v_add_u32_e32 v42, -1, v38
	v_add_u32_e32 v46, 1, v38
	v_fma_f32 v56, -v42, v38, v34
	v_fma_f32 v57, -v46, v38, v34
	v_cmp_ge_f32_e64 s[0:1], 0, v56
	v_pk_fma_f32 v[36:37], v[168:169], v[50:51], v[36:37] op_sel_hi:[1,0,1] neg_lo:[1,0,0] neg_hi:[1,0,0]
	s_nop 0
	v_cndmask_b32_e64 v38, v38, v42, s[0:1]
	v_cmp_lt_f32_e64 s[0:1], 0, v57
	s_nop 1
	v_cndmask_b32_e64 v38, v38, v46, s[0:1]
	v_mul_f32_e32 v42, 0x37800000, v38
	v_cndmask_b32_e32 v38, v38, v42, vcc
	v_cmp_class_f32_e32 vcc, v34, v186
	s_nop 1
	v_cndmask_b32_e32 v34, v38, v34, vcc
	v_div_scale_f32 v38, s[0:1], v34, v34, 1.0
	v_rcp_f32_e32 v42, v38
	v_div_scale_f32 v46, vcc, 1.0, v34, 1.0
	v_fma_f32 v56, -v38, v42, 1.0
	v_fmac_f32_e32 v42, v56, v42
	v_mul_f32_e32 v56, v46, v42
	v_fma_f32 v57, -v38, v56, v46
	v_fmac_f32_e32 v56, v57, v42
	v_fma_f32 v38, -v38, v56, v46
	v_div_fmas_f32 v38, v38, v42, v56
	v_div_fixup_f32 v34, v38, v34, 1.0
	v_pk_fma_f32 v[40:41], v[40:41], v[34:35], v[68:69] op_sel_hi:[1,0,1]
	v_pk_fma_f32 v[32:33], v[32:33], v[34:35], v[128:129] op_sel_hi:[1,0,1]
; __device__ __forceinline__ unsigned cvt_pk_bf16(float lo, float hi) { unsigned r; asm volatile("v_cvt_pk_bf16_f32 %0, %1, %2" : "=v"(r) : "v"(lo), "v"(hi)); return r; }
; __device__ __forceinline__ float siluf_(float x) { return x * sigmoidf_(x); }
; __device__ __forceinline__ f32x2 ln_stats(f32x2 sm) { const float mu = sm[0] * (1.f / D); const float var = fmaxf(sm[1] * (1.f / D) - mu * mu, 0.f); return (f32x2){mu, 1.0f / sqrtf(var + LN_EPS)}; }
;     __device__ __forceinline__ void operator()(const f32x4 (&acc)[2][2][4][2], const Unit& u, int wr, int wc, int fr, int fq) const {
;     ...
;         for (int ai = 0; ai < 2; ++ai)
; #pragma unroll
;             for (int m = 0; m < 4; ++m) {
;                 const int r = row0 + ai * HALF + m * 16;
;                 bf16_t* rowp = H + (size_t)r * ldh + col0;
;                 f32x2 st = (f32x2){0.f, 1.f};
;                 if (rsum) st = ln_stats(*(const f32x2*)(rsum + 2 * (size_t)r));
;                 f32x4 v0, v1;
; #pragma unroll
;                 for (int j = 0; j < 4; ++j) {
;                     const float g0 = st[1] * (acc[ai][0][m][0][j] - st[0] * s1[0][0][j]) + s2[0][0][j], u0 = st[1] * (acc[ai][1][m][0][j] - st[0] * s1[1][0][j]) + s2[1][0][j];
;                     const float g1 = st[1] * (acc[ai][0][m][1][j] - st[0] * s1[0][1][j]) + s2[0][1][j], u1 = st[1] * (acc[ai][1][m][1][j] - st[0] * s1[1][1][j]) + s2[1][1][j];
;                     v0[j] = siluf_(g0) * u0; v1[j] = siluf_(g1) * u1;
;                 }
;                 u32x4 w; w.x = cvt_pk_bf16(v0[0], v0[1]); w.y = cvt_pk_bf16(v0[2], v0[3]); w.z = cvt_pk_bf16(v1[0], v1[1]); w.w = cvt_pk_bf16(v1[2], v1[3]);
;                 *(u32x4*)rowp = w;
	v_pk_fma_f32 v[54:55], v[54:55], v[34:35], v[164:165] op_sel_hi:[1,0,1]
	v_pk_fma_f32 v[44:45], v[44:45], v[34:35], v[72:73] op_sel_hi:[1,0,1]
	v_mul_f32_e32 v56, 0xbfb8aa3b, v41
	v_mul_f32_e32 v57, 0xbfb8aa3b, v33
	v_pk_fma_f32 v[52:53], v[52:53], v[34:35], v[132:133] op_sel_hi:[1,0,1]
	v_mul_f32_e32 v42, 0xbfb8aa3b, v55
	v_mul_f32_e32 v46, 0xbfb8aa3b, v45
	v_exp_f32_e32 v56, v56
	v_exp_f32_e32 v57, v57
	v_mul_f32_e32 v38, 0xbfb8aa3b, v53
	v_exp_f32_e32 v42, v42
	v_exp_f32_e32 v46, v46
	v_exp_f32_e32 v38, v38
	v_pk_fma_f32 v[36:37], v[36:37], v[34:35], v[136:137] op_sel_hi:[1,0,1]
	v_add_f32_e32 v56, 1.0, v56
	v_add_f32_e32 v57, 1.0, v57
	v_mul_f32_e32 v58, 0xbfb8aa3b, v37
	v_add_f32_e32 v42, 1.0, v42
	v_add_f32_e32 v46, 1.0, v46
	v_rcp_f32_e32 v56, v56
	v_rcp_f32_e32 v57, v57
	v_exp_f32_e32 v58, v58
	v_add_f32_e32 v38, 1.0, v38
	v_rcp_f32_e32 v42, v42
	v_rcp_f32_e32 v46, v46
	v_rcp_f32_e32 v38, v38
	v_mul_f32_e32 v41, v41, v56
	v_mul_f32_e32 v33, v33, v57
	v_mul_f32_e32 v42, v55, v42
	v_mul_f32_e32 v45, v45, v46
	v_mul_f32_e32 v40, v40, v41
	v_mul_f32_e32 v41, v32, v33
	v_add_f32_e32 v32, 1.0, v58
	v_mov_b32_e32 v46, v39
	v_mul_f32_e32 v38, v53, v38
	v_mul_f32_e32 v53, v54, v42
	v_mul_f32_e32 v44, v44, v45
	v_rcp_f32_e32 v45, v32
	v_pk_fma_f32 v[32:33], v[78:79], v[50:51], v[46:47] op_sel_hi:[1,0,1] neg_lo:[1,0,0] neg_hi:[1,0,0]
	v_mov_b32_e32 v42, v35
	v_mul_f32_e32 v52, v52, v38
	v_pk_fma_f32 v[32:33], v[32:33], v[34:35], v[74:75] op_sel_hi:[1,0,1]
	v_pk_fma_f32 v[38:39], v[66:67], v[50:51], v[42:43] op_sel_hi:[1,0,1] neg_lo:[1,0,0] neg_hi:[1,0,0]
	v_mul_f32_e32 v37, v37, v45
	v_pk_fma_f32 v[34:35], v[38:39], v[34:35], v[70:71] op_sel_hi:[1,0,1]
	v_mul_f32_e32 v38, 0xbfb8aa3b, v33
	v_exp_f32_e32 v38, v38
	v_mul_f32_e32 v39, 0xbfb8aa3b, v35
	v_exp_f32_e32 v39, v39
	v_mul_f32_e32 v36, v36, v37
	v_add_f32_e32 v38, 1.0, v38
	v_rcp_f32_e32 v38, v38
	v_add_f32_e32 v39, 1.0, v39
	v_rcp_f32_e32 v39, v39
	v_mov_b32_e32 v37, v24
	v_mul_f32_e32 v33, v33, v38
	v_mul_f32_e32 v33, v32, v33
	v_mul_f32_e32 v32, v35, v39
	v_mul_f32_e32 v35, v34, v32
	v_cvt_pk_bf16_f32 v32, v52, v44
	v_cvt_pk_bf16_f32 v33, v41, v33
	v_cvt_pk_bf16_f32 v34, v53, v40
	v_cvt_pk_bf16_f32 v35, v36, v35
	global_store_dwordx4 v[48:49], v[32:35], off
	v_mov_b32_e32 v38, v16
	v_mov_b32_e32 v39, v20
	v_add_u32_e32 v32, 0xa0, v162
	v_ashrrev_i32_e32 v33, 31, v32
	v_lshl_add_u64 v[34:35], v[32:33], 3, s[8:9]
	v_mov_b32_e32 v34, v248
	v_mov_b32_e32 v35, v249
	v_mov_b32_e32 v20, v17
	v_mov_b32_e32 v16, v30
	v_mov_b32_e32 v17, v26
	v_mov_b32_e32 v26, v31
	v_mad_i64_i32 v[30:31], s[0:1], v32, s53, v[160:161]
	v_mov_b32_e32 v36, v28
	v_mov_b32_e32 v28, v18
	v_mov_b32_e32 v24, v29
	v_mov_b32_e32 v29, v22
	v_lshl_add_u64 v[30:31], v[30:31], 0, v[170:171]
	s_nop 0
	v_pk_mul_f32 v[32:33], v[34:35], s[20:21] op_sel_hi:[1,0]
	s_nop 0
	v_fma_f32 v18, -v32, v32, v33
	v_max_f32_e32 v18, 0, v18
	v_add_f32_e32 v18, 0x3727c5ac, v18
	v_mul_f32_e32 v22, 0x4f800000, v18
	v_cmp_gt_f32_e32 vcc, s54, v18
	v_pk_fma_f32 v[34:35], v[172:173], v[32:33], v[36:37] op_sel_hi:[1,0,1] neg_lo:[1,0,0] neg_hi:[1,0,0]
	v_pk_fma_f32 v[36:37], v[174:175], v[32:33], v[38:39] op_sel_hi:[1,0,1] neg_lo:[1,0,0] neg_hi:[1,0,0]
	v_cndmask_b32_e32 v18, v18, v22, vcc
	v_sqrt_f32_e32 v22, v18
	v_pk_fma_f32 v[16:17], v[166:167], v[32:33], v[16:17] op_sel_hi:[1,0,1] neg_lo:[1,0,0] neg_hi:[1,0,0]
	v_pk_fma_f32 v[24:25], v[76:77], v[32:33], v[24:25] op_sel_hi:[1,0,1] neg_lo:[1,0,0] neg_hi:[1,0,0]
	v_pk_fma_f32 v[20:21], v[64:65], v[32:33], v[20:21] op_sel_hi:[1,0,1] neg_lo:[1,0,0] neg_hi:[1,0,0]
	v_add_u32_e32 v38, -1, v22
	v_add_u32_e32 v39, 1, v22
	v_fma_f32 v40, -v38, v22, v18
	v_fma_f32 v41, -v39, v22, v18
	v_cmp_ge_f32_e64 s[0:1], 0, v40
	v_pk_fma_f32 v[28:29], v[168:169], v[32:33], v[28:29] op_sel_hi:[1,0,1] neg_lo:[1,0,0] neg_hi:[1,0,0]
	s_nop 0
	v_cndmask_b32_e64 v22, v22, v38, s[0:1]
	v_cmp_lt_f32_e64 s[0:1], 0, v41
	s_nop 1
	v_cndmask_b32_e64 v22, v22, v39, s[0:1]
	v_mul_f32_e32 v38, 0x37800000, v22
	v_cndmask_b32_e32 v22, v22, v38, vcc
	v_cmp_class_f32_e32 vcc, v18, v186
	s_nop 1
	v_cndmask_b32_e32 v18, v22, v18, vcc
	v_div_scale_f32 v22, s[0:1], v18, v18, 1.0
	v_rcp_f32_e32 v38, v22
	v_div_scale_f32 v39, vcc, 1.0, v18, 1.0
	v_fma_f32 v40, -v22, v38, 1.0
	v_fmac_f32_e32 v38, v40, v38
	v_mul_f32_e32 v40, v39, v38
	v_fma_f32 v41, -v22, v40, v39
	v_fmac_f32_e32 v40, v41, v38
	v_fma_f32 v22, -v22, v40, v39
	v_div_fmas_f32 v22, v22, v38, v40
	v_div_fixup_f32 v18, v22, v18, 1.0
	v_pk_fma_f32 v[34:35], v[34:35], v[18:19], v[132:133] op_sel_hi:[1,0,1]
	v_pk_fma_f32 v[36:37], v[36:37], v[18:19], v[164:165] op_sel_hi:[1,0,1]
	v_pk_fma_f32 v[16:17], v[16:17], v[18:19], v[128:129] op_sel_hi:[1,0,1]
	v_pk_fma_f32 v[24:25], v[24:25], v[18:19], v[72:73] op_sel_hi:[1,0,1]
	v_pk_fma_f32 v[20:21], v[20:21], v[18:19], v[68:69] op_sel_hi:[1,0,1]
	v_mul_f32_e32 v22, 0xbfb8aa3b, v35
	v_mul_f32_e32 v38, 0xbfb8aa3b, v37
	v_mul_f32_e32 v41, 0xbfb8aa3b, v17
	v_mul_f32_e32 v39, 0xbfb8aa3b, v25
	v_mul_f32_e32 v40, 0xbfb8aa3b, v21
	v_exp_f32_e32 v22, v22
	v_exp_f32_e32 v38, v38
	v_exp_f32_e32 v41, v41
	v_exp_f32_e32 v39, v39
	v_exp_f32_e32 v40, v40
	v_add_f32_e32 v22, 1.0, v22
	v_add_f32_e32 v38, 1.0, v38
	v_add_f32_e32 v41, 1.0, v41
	v_add_f32_e32 v39, 1.0, v39
	v_add_f32_e32 v40, 1.0, v40
	v_rcp_f32_e32 v22, v22
	v_rcp_f32_e32 v38, v38
	v_rcp_f32_e32 v41, v41
	v_rcp_f32_e32 v39, v39
	v_rcp_f32_e32 v40, v40
	v_mul_f32_e32 v22, v35, v22
	v_mul_f32_e32 v35, v37, v38
	v_mul_f32_e32 v17, v17, v41
	v_mul_f32_e32 v25, v25, v39
	v_mul_f32_e32 v21, v21, v40
	v_mul_f32_e32 v34, v34, v22
	v_mul_f32_e32 v35, v36, v35
	v_mul_f32_e32 v36, v16, v17
; __device__ __forceinline__ unsigned cvt_pk_bf16(float lo, float hi) { unsigned r; asm volatile("v_cvt_pk_bf16_f32 %0, %1, %2" : "=v"(r) : "v"(lo), "v"(hi)); return r; }
; __device__ __forceinline__ float siluf_(float x) { return x * sigmoidf_(x); }
; #define PG8_BAR __builtin_amdgcn_s_barrier()
; template <class Sched, class Epi, bool ALIGN_EPI, bool SP2>
; __device__ __forceinline__ void gemm_phase(LAS unsigned char* lds, const int K, const int lda, const int ldb, const Sched& S, const Epi& E) {
;     ...
;         if (!has_next) break;
;         bool keep = false;
;         if constexpr (Epi::CAN_KEEP) keep = (cur.kind < 2);
;         if (!keep) {
; #pragma unroll
;         for (int a = 0; a < 2; ++a)
; #pragma unroll
;             for (int b = 0; b < 2; ++b)
; #pragma unroll
;                 for (int m = 0; m < 4; ++m)
; #pragma unroll
;                     for (int n = 0; n < 2; ++n) acc[a][b][m][n] = (f32x4){0.f, 0.f, 0.f, 0.f};
;         }
;         cur = nxt; cA = nA; cB = nB; ++ui;
;         if constexpr (ALIGN_EPI) { if (wr == 1) PG8_BAR; }
;     __device__ __forceinline__ void operator()(const f32x4 (&acc)[2][2][4][2], const Unit& u, int wr, int wc, int fr, int fq) const {
;     ...
;         for (int ai = 0; ai < 2; ++ai)
; #pragma unroll
;             for (int m = 0; m < 4; ++m) {
;                 const int r = row0 + ai * HALF + m * 16;
;                 bf16_t* rowp = H + (size_t)r * ldh + col0;
;                 f32x2 st = (f32x2){0.f, 1.f};
;                 if (rsum) st = ln_stats(*(const f32x2*)(rsum + 2 * (size_t)r));
;                 f32x4 v0, v1;
; #pragma unroll
;                 for (int j = 0; j < 4; ++j) {
;                     const float g0 = st[1] * (acc[ai][0][m][0][j] - st[0] * s1[0][0][j]) + s2[0][0][j], u0 = st[1] * (acc[ai][1][m][0][j] - st[0] * s1[1][0][j]) + s2[1][0][j];
;                     const float g1 = st[1] * (acc[ai][0][m][1][j] - st[0] * s1[0][1][j]) + s2[0][1][j], u1 = st[1] * (acc[ai][1][m][1][j] - st[0] * s1[1][1][j]) + s2[1][1][j];
;                     v0[j] = siluf_(g0) * u0; v1[j] = siluf_(g1) * u1;
;                 }
;                 u32x4 w; w.x = cvt_pk_bf16(v0[0], v0[1]); w.y = cvt_pk_bf16(v0[2], v0[3]); w.z = cvt_pk_bf16(v1[0], v1[1]); w.w = cvt_pk_bf16(v1[2], v1[3]);
;                 *(u32x4*)rowp = w;
	v_pk_fma_f32 v[16:17], v[78:79], v[32:33], v[26:27] op_sel_hi:[1,0,1] neg_lo:[1,0,0] neg_hi:[1,0,0]
	v_mov_b32_e32 v22, v19
	v_mul_f32_e32 v24, v24, v25
	v_mul_f32_e32 v25, v20, v21
	v_pk_fma_f32 v[16:17], v[16:17], v[18:19], v[74:75] op_sel_hi:[1,0,1]
	v_pk_fma_f32 v[20:21], v[66:67], v[32:33], v[22:23] op_sel_hi:[1,0,1] neg_lo:[1,0,0] neg_hi:[1,0,0]
	v_pk_fma_f32 v[28:29], v[28:29], v[18:19], v[136:137] op_sel_hi:[1,0,1]
	v_pk_fma_f32 v[18:19], v[20:21], v[18:19], v[70:71] op_sel_hi:[1,0,1]
	v_mul_f32_e32 v20, 0xbfb8aa3b, v17
	v_exp_f32_e32 v20, v20
	v_mul_f32_e32 v21, 0xbfb8aa3b, v19
	v_mul_f32_e32 v42, 0xbfb8aa3b, v29
	v_exp_f32_e32 v21, v21
	v_exp_f32_e32 v42, v42
	v_add_f32_e32 v20, 1.0, v20
	v_rcp_f32_e32 v20, v20
	v_add_f32_e32 v21, 1.0, v21
	v_add_f32_e32 v42, 1.0, v42
	v_rcp_f32_e32 v21, v21
	v_rcp_f32_e32 v42, v42
	v_mul_f32_e32 v17, v17, v20
	v_mul_f32_e32 v17, v16, v17
	v_mul_f32_e32 v16, v19, v21
	v_mul_f32_e32 v22, v29, v42
	v_mul_f32_e32 v19, v18, v16
	v_cvt_pk_bf16_f32 v16, v34, v24
	v_mul_f32_e32 v22, v28, v22
	v_cvt_pk_bf16_f32 v17, v36, v17
	v_cvt_pk_bf16_f32 v18, v35, v25
	v_cvt_pk_bf16_f32 v19, v22, v19
	global_store_dwordx4 v[30:31], v[16:19], off
	v_mov_b32_e32 v22, v4
	v_mov_b32_e32 v23, v0
	v_add_u32_e32 v16, 0xb0, v162
	v_ashrrev_i32_e32 v17, 31, v16
	v_lshl_add_u64 v[18:19], v[16:17], 3, s[8:9]
	v_mov_b32_e32 v18, v250
	v_mov_b32_e32 v19, v251
	v_mov_b32_e32 v0, v5
	v_mov_b32_e32 v4, v14
	v_mov_b32_e32 v5, v10
	v_mov_b32_e32 v10, v15
	v_mov_b32_e32 v20, v12
	v_mov_b32_e32 v21, v8
	v_mov_b32_e32 v8, v13
	v_mov_b32_e32 v12, v6
	v_mov_b32_e32 v13, v2
	v_mov_b32_e32 v2, v7
	v_mad_i64_i32 v[6:7], s[0:1], v16, s53, v[160:161]
	v_lshl_add_u64 v[6:7], v[6:7], 0, v[170:171]
	s_nop 0
	v_pk_mul_f32 v[14:15], v[18:19], s[20:21] op_sel_hi:[1,0]
	s_nop 0
	v_fma_f32 v24, -v14, v14, v15
	v_pk_fma_f32 v[16:17], v[172:173], v[14:15], v[20:21] op_sel_hi:[1,0,1] neg_lo:[1,0,0] neg_hi:[1,0,0]
	v_max_f32_e32 v20, 0, v24
	v_add_f32_e32 v20, 0x3727c5ac, v20
	v_mul_f32_e32 v21, 0x4f800000, v20
	v_cmp_gt_f32_e32 vcc, s54, v20
	v_pk_fma_f32 v[18:19], v[174:175], v[14:15], v[22:23] op_sel_hi:[1,0,1] neg_lo:[1,0,0] neg_hi:[1,0,0]
	v_pk_fma_f32 v[8:9], v[76:77], v[14:15], v[8:9] op_sel_hi:[1,0,1] neg_lo:[1,0,0] neg_hi:[1,0,0]
	v_cndmask_b32_e32 v20, v20, v21, vcc
	v_sqrt_f32_e32 v21, v20
	v_pk_fma_f32 v[0:1], v[64:65], v[14:15], v[0:1] op_sel_hi:[1,0,1] neg_lo:[1,0,0] neg_hi:[1,0,0]
	v_pk_fma_f32 v[4:5], v[166:167], v[14:15], v[4:5] op_sel_hi:[1,0,1] neg_lo:[1,0,0] neg_hi:[1,0,0]
	v_pk_fma_f32 v[12:13], v[168:169], v[14:15], v[12:13] op_sel_hi:[1,0,1] neg_lo:[1,0,0] neg_hi:[1,0,0]
	v_add_u32_e32 v22, -1, v21
	v_add_u32_e32 v23, 1, v21
	v_fma_f32 v24, -v22, v21, v20
	v_fma_f32 v25, -v23, v21, v20
	v_cmp_ge_f32_e64 s[0:1], 0, v24
	v_pk_fma_f32 v[10:11], v[78:79], v[14:15], v[10:11] op_sel_hi:[1,0,1] neg_lo:[1,0,0] neg_hi:[1,0,0]
	s_nop 0
	v_cndmask_b32_e64 v21, v21, v22, s[0:1]
	v_cmp_lt_f32_e64 s[0:1], 0, v25
	s_nop 1
	v_cndmask_b32_e64 v21, v21, v23, s[0:1]
	v_mul_f32_e32 v22, 0x37800000, v21
	v_cndmask_b32_e32 v21, v21, v22, vcc
	v_cmp_class_f32_e32 vcc, v20, v186
	s_nop 1
	v_cndmask_b32_e32 v20, v21, v20, vcc
	v_div_scale_f32 v21, s[0:1], v20, v20, 1.0
	v_rcp_f32_e32 v22, v21
	v_div_scale_f32 v23, vcc, 1.0, v20, 1.0
	s_mov_b64 s[0:1], -1
	v_fma_f32 v24, -v21, v22, 1.0
	v_fmac_f32_e32 v22, v24, v22
	v_mul_f32_e32 v24, v23, v22
	v_fma_f32 v25, -v21, v24, v23
	v_fmac_f32_e32 v24, v25, v22
	v_fma_f32 v21, -v21, v24, v23
	v_div_fmas_f32 v21, v21, v22, v24
	v_div_fixup_f32 v20, v21, v20, 1.0
	v_pk_fma_f32 v[8:9], v[8:9], v[20:21], v[72:73] op_sel_hi:[1,0,1]
	v_pk_fma_f32 v[0:1], v[0:1], v[20:21], v[68:69] op_sel_hi:[1,0,1]
	v_mul_f32_e32 v23, 0xbfb8aa3b, v9
	v_mul_f32_e32 v24, 0xbfb8aa3b, v1
	v_pk_fma_f32 v[16:17], v[16:17], v[20:21], v[132:133] op_sel_hi:[1,0,1]
	v_exp_f32_e32 v23, v23
	v_exp_f32_e32 v24, v24
	v_pk_fma_f32 v[18:19], v[18:19], v[20:21], v[164:165] op_sel_hi:[1,0,1]
	v_pk_fma_f32 v[4:5], v[4:5], v[20:21], v[128:129] op_sel_hi:[1,0,1]
	v_pk_fma_f32 v[12:13], v[12:13], v[20:21], v[136:137] op_sel_hi:[1,0,1]
	v_pk_fma_f32 v[10:11], v[10:11], v[20:21], v[74:75] op_sel_hi:[1,0,1]
	v_mul_f32_e32 v21, 0xbfb8aa3b, v17
	v_exp_f32_e32 v21, v21
	v_add_f32_e32 v23, 1.0, v23
	v_add_f32_e32 v24, 1.0, v24
	v_rcp_f32_e32 v23, v23
	v_rcp_f32_e32 v24, v24
	v_add_f32_e32 v21, 1.0, v21
	v_rcp_f32_e32 v21, v21
	v_mul_f32_e32 v9, v9, v23
	v_mul_f32_e32 v1, v1, v24
	v_mul_f32_e32 v8, v8, v9
	v_mul_f32_e32 v9, v0, v1
	v_pk_fma_f32 v[0:1], v[66:67], v[14:15], v[2:3] op_sel_hi:[1,0,1] neg_lo:[1,0,0] neg_hi:[1,0,0]
	v_mul_f32_e32 v25, 0xbfb8aa3b, v5
	v_pk_fma_f32 v[0:1], v[0:1], v[20:21], v[70:71] op_sel_hi:[1,0,1]
	v_mul_f32_e32 v2, 0xbfb8aa3b, v11
	v_mul_f32_e32 v3, 0xbfb8aa3b, v1
	v_mul_f32_e32 v22, 0xbfb8aa3b, v19
	v_mul_f32_e32 v26, 0xbfb8aa3b, v13
	v_exp_f32_e32 v25, v25
	v_exp_f32_e32 v2, v2
	v_exp_f32_e32 v3, v3
	v_exp_f32_e32 v22, v22
	v_exp_f32_e32 v26, v26
	v_add_f32_e32 v25, 1.0, v25
	v_add_f32_e32 v2, 1.0, v2
	v_add_f32_e32 v3, 1.0, v3
	v_add_f32_e32 v22, 1.0, v22
	v_add_f32_e32 v26, 1.0, v26
	v_rcp_f32_e32 v25, v25
	v_rcp_f32_e32 v2, v2
	v_rcp_f32_e32 v3, v3
	v_rcp_f32_e32 v22, v22
	v_rcp_f32_e32 v26, v26
	v_mul_f32_e32 v5, v5, v25
	v_mul_f32_e32 v2, v11, v2
	v_mul_f32_e32 v1, v1, v3
	v_mul_f32_e32 v17, v17, v21
	v_mul_f32_e32 v19, v19, v22
	v_mul_f32_e32 v4, v4, v5
	v_mul_f32_e32 v5, v13, v26
	v_mul_f32_e32 v2, v10, v2
	v_mul_f32_e32 v3, v0, v1
	s_andn2_b64 vcc, exec, s[22:23]
	v_mul_f32_e32 v16, v16, v17
	v_mul_f32_e32 v17, v18, v19
	v_mul_f32_e32 v5, v12, v5
	v_cvt_pk_bf16_f32 v0, v16, v8
	v_cvt_pk_bf16_f32 v1, v4, v2
	v_cvt_pk_bf16_f32 v2, v17, v9
	v_cvt_pk_bf16_f32 v3, v5, v3
	global_store_dwordx4 v[6:7], v[0:3], off
	s_cbranch_vccnz .LBB0_1029
	s_andn2_b64 vcc, exec, s[4:5]
	s_cbranch_vccnz .LBB0_1028
	s_barrier
	s_branch .LBB0_1028
